# v024 + non-temporal hint on the read-once epilogue loads of the out-projection and PLE-gate GEMMs
# baseline (speedup 1.0000x reference)
; __device__ __forceinline__ int fresh_lane() { int l; asm volatile("v_mbcnt_lo_u32_b32 %0, -1, 0\n\tv_mbcnt_hi_u32_b32 %0, -1, %0" : "=v"(l)); return l; }
;     __device__ __forceinline__ void operator()(accv (&acc)[2][2][4][2], const pg8::Unit& u, int wr, int wc, int fr, int fq) const {
;         { const int ln_ = fresh_lane(); fr = ln_ & 15; fq = ln_ >> 4; }
;         const int rowb = u.pm * 256 + wr * 64 + fr, col0 = u.pn * 256 + wc * 32 + 8 * fq;
; #pragma unroll
;         for (int ai = 0; ai < 2; ++ai)
; #pragma unroll
;             for (int m = 0; m < 4; ++m) {
;                 const int row = rowb + 128 * ai + 16 * m; float s = 0.f;
; #pragma unroll
;                 for (int bj = 0; bj < 2; ++bj) {
;                     const size_t off = (size_t)row * D + col0 + 128 * bj;
;                     F8 bs; if (basef) { bs.a = *(const f32x4*)(basef + off); bs.b = *(const f32x4*)(basef + off + 4); } else bs = split_load8(bhi, blo, off);
.LBB0_1284:
	s_lshl_b32 s0, s4, 8
	s_add_i32 s0, s0, s70
	v_mbcnt_lo_u32_b32 v166, -1, 0
	v_mbcnt_hi_u32_b32 v166, -1, v166
	s_andn2_b64 vcc, exec, s[48:49]
	v_and_or_b32 v150, v166, 15, s0
	s_lshl_b32 s0, s58, 8
	v_ashrrev_i32_e32 v132, 1, v166
	s_or_b32 s0, s0, s71
	v_and_b32_e32 v132, -8, v132
	v_add_u32_e32 v148, s0, v132
	v_ashrrev_i32_e32 v151, 31, v150
	v_ashrrev_i32_e32 v149, 31, v148
	v_lshlrev_b64 v[132:133], 10, v[150:151]
	v_lshl_add_u64 v[152:153], v[132:133], 0, v[148:149]
	v_cndmask_b32_e64 v132, 0, 1, s[48:49]
	v_cmp_ne_u32_e64 s[10:11], 1, v132
	v_lshl_add_u64 v[156:157], v[152:153], 2, s[20:21]
	s_cbranch_vccnz .LBB0_1286
	global_load_dwordx4 v[136:139], v[156:157], off offset:16 nt
	global_load_dwordx4 v[132:135], v[156:157], off nt
	s_mov_b64 s[4:5], 0
	s_branch .LBB0_1287

; __device__ __forceinline__ unsigned cvtpk(float lo, float hi) { f32x2_t v = {lo, hi}; bf16x2_t b = __builtin_convertvector(v, bf16x2_t); return __builtin_bit_cast(unsigned, b); }
; __device__ __forceinline__ void split_store8(bf16* hi, bf16* lo, size_t off, const F8& v) {
;     const v4u h = (v4u){cvtpk(v.a[0], v.a[1]), cvtpk(v.a[2], v.a[3]), cvtpk(v.b[0], v.b[1]), cvtpk(v.b[2], v.b[3])};
;     f32x4 ha, hb; unpack8(h, ha, hb);
;     const f32x4 ra = v.a - ha, rb = v.b - hb;
;     *(v4u*)(hi + off) = h;
;     *(v4u*)(lo + off) = (v4u){cvtpk(ra[0], ra[1]), cvtpk(ra[2], ra[3]), cvtpk(rb[0], rb[1]), cvtpk(rb[2], rb[3])};
; }
; __device__ __forceinline__ F8 split_load8(const bf16* hi, const bf16* lo, size_t off) {
;     const v4u h = *(const v4u*)(hi + off), l = *(const v4u*)(lo + off);
;     f32x4 ha, hb, la, lb; unpack8(h, ha, hb); unpack8(l, la, lb);
;     return F8{ha + la, hb + lb};
; }
;     __device__ __forceinline__ void operator()(accv (&acc)[2][2][4][2], const pg8::Unit& u, int wr, int wc, int fr, int fq) const {
;     ...
;                 const int row = rowb + 128 * ai + 16 * m; float s = 0.f;
; #pragma unroll
;                 for (int bj = 0; bj < 2; ++bj) {
;                     const size_t off = (size_t)row * D + col0 + 128 * bj;
;                     F8 bs; if (basef) { bs.a = *(const f32x4*)(basef + off); bs.b = *(const f32x4*)(basef + off + 4); } else bs = split_load8(bhi, blo, off);
;                     F8 v; v.a = bs.a + acc[ai][bj][m][0]; v.b = bs.b + acc[ai][bj][m][1];
;                     split_store8(ohi, olo, off, v);
;                     s += ((v.a[0] * v.a[0] + v.a[1] * v.a[1]) + (v.a[2] * v.a[2] + v.a[3] * v.a[3])) + ((v.b[0] * v.b[0] + v.b[1] * v.b[1]) + (v.b[2] * v.b[2] + v.b[3] * v.b[3]));
.LBB0_1287:
	v_lshlrev_b64 v[162:163], 1, v[152:153]
	s_andn2_b64 vcc, exec, s[4:5]
	v_lshl_add_u64 v[152:153], s[40:41], 0, v[162:163]
	v_lshl_add_u64 v[154:155], s[16:17], 0, v[162:163]
	s_cbranch_vccnz .LBB0_1289
	global_load_dwordx4 v[132:135], v[152:153], off nt
	global_load_dwordx4 v[136:139], v[154:155], off nt
	s_waitcnt vmcnt(0)
	v_lshlrev_b32_e32 v158, 16, v132
	v_and_b32_e32 v159, 0xffff0000, v132
	v_lshlrev_b32_e32 v132, 16, v133
	v_and_b32_e32 v133, 0xffff0000, v133
	v_lshlrev_b32_e32 v160, 16, v134
	v_and_b32_e32 v161, 0xffff0000, v134
	v_lshlrev_b32_e32 v168, 16, v135
	v_and_b32_e32 v169, 0xffff0000, v135
	v_lshlrev_b32_e32 v170, 16, v136
	v_and_b32_e32 v171, 0xffff0000, v136
	v_lshlrev_b32_e32 v134, 16, v137
	v_and_b32_e32 v135, 0xffff0000, v137
	v_lshlrev_b32_e32 v136, 16, v138
	v_and_b32_e32 v137, 0xffff0000, v138
	v_lshlrev_b32_e32 v138, 16, v139
	v_and_b32_e32 v139, 0xffff0000, v139
	v_pk_add_f32 v[134:135], v[132:133], v[134:135]
	v_pk_add_f32 v[132:133], v[158:159], v[170:171]
	v_pk_add_f32 v[138:139], v[168:169], v[138:139]
	v_pk_add_f32 v[136:137], v[160:161], v[136:137]
.LBB0_1289:
	s_waitcnt vmcnt(0)
	v_pk_add_f32 v[158:159], v[130:131], v[134:135]
	v_pk_add_f32 v[160:161], v[128:129], v[132:133]
	v_pk_add_f32 v[138:139], v[126:127], v[138:139]
	v_pk_add_f32 v[136:137], v[124:125], v[136:137]
	v_cvt_pk_bf16_f32 v124, v160, v161
	v_cvt_pk_bf16_f32 v125, v158, v159
	v_cvt_pk_bf16_f32 v126, v136, v137
	v_cvt_pk_bf16_f32 v127, v138, v139
	v_lshlrev_b32_e32 v128, 16, v124
	v_and_b32_e32 v129, 0xffff0000, v124
	v_lshlrev_b32_e32 v130, 16, v125
	v_and_b32_e32 v131, 0xffff0000, v125
	v_lshlrev_b32_e32 v132, 16, v126
	v_and_b32_e32 v133, 0xffff0000, v126
	v_lshlrev_b32_e32 v134, 16, v127
	v_and_b32_e32 v135, 0xffff0000, v127
	v_sub_f32_e32 v131, v159, v131
	v_sub_f32_e32 v130, v158, v130
	v_sub_f32_e32 v129, v161, v129
	v_sub_f32_e32 v128, v160, v128
	v_sub_f32_e32 v167, v139, v135
	v_sub_f32_e32 v168, v138, v134
	v_sub_f32_e32 v133, v137, v133
	v_sub_f32_e32 v132, v136, v132
	v_lshl_add_u64 v[134:135], s[42:43], 0, v[162:163]
	global_store_dwordx4 v[134:135], v[124:127], off
	s_and_b64 vcc, exec, s[10:11]
	s_nop 0
	v_cvt_pk_bf16_f32 v124, v128, v129
	v_cvt_pk_bf16_f32 v125, v130, v131
	v_cvt_pk_bf16_f32 v126, v132, v133
	v_cvt_pk_bf16_f32 v127, v168, v167
	v_lshl_add_u64 v[132:133], s[44:45], 0, v[162:163]
	global_store_dwordx4 v[132:133], v[124:127], off
	s_cbranch_vccnz .LBB0_1296
	global_load_dwordx4 v[128:131], v[156:157], off offset:528 nt
	global_load_dwordx4 v[124:127], v[156:157], off offset:512 nt
	s_cbranch_execnz .LBB0_1292
.LBB0_1291:
	global_load_dwordx4 v[124:127], v[152:153], off offset:256 nt
	global_load_dwordx4 v[128:131], v[154:155], off offset:256 nt
	s_waitcnt vmcnt(1)
	v_lshlrev_b32_e32 v152, 16, v124
	v_and_b32_e32 v153, 0xffff0000, v124
	v_lshlrev_b32_e32 v124, 16, v125
	v_and_b32_e32 v125, 0xffff0000, v125
	v_lshlrev_b32_e32 v154, 16, v126
	v_and_b32_e32 v155, 0xffff0000, v126
	v_lshlrev_b32_e32 v156, 16, v127
	v_and_b32_e32 v157, 0xffff0000, v127
	s_waitcnt vmcnt(0)
	v_lshlrev_b32_e32 v162, 16, v128
	v_and_b32_e32 v163, 0xffff0000, v128
	v_lshlrev_b32_e32 v126, 16, v129
	v_and_b32_e32 v127, 0xffff0000, v129
	v_lshlrev_b32_e32 v128, 16, v130
	v_and_b32_e32 v129, 0xffff0000, v130
	v_lshlrev_b32_e32 v130, 16, v131
	v_and_b32_e32 v131, 0xffff0000, v131
	v_pk_add_f32 v[126:127], v[124:125], v[126:127]
	v_pk_add_f32 v[124:125], v[152:153], v[162:163]
	v_pk_add_f32 v[130:131], v[156:157], v[130:131]
	v_pk_add_f32 v[128:129], v[154:155], v[128:129]

;     __device__ __forceinline__ void operator()(accv (&acc)[2][2][4][2], const pg8::Unit& u, int wr, int wc, int fr, int fq) const {
;     ...
;                 const int row = rowb + 128 * ai + 16 * m; float s = 0.f;
; #pragma unroll
;                 for (int bj = 0; bj < 2; ++bj) {
;                     const size_t off = (size_t)row * D + col0 + 128 * bj;
;                     F8 bs; if (basef) { bs.a = *(const f32x4*)(basef + off); bs.b = *(const f32x4*)(basef + off + 4); } else bs = split_load8(bhi, blo, off);
.LBB0_1294:
	s_or_b64 exec, exec, s[4:5]
	v_or_b32_e32 v124, 16, v150
	v_ashrrev_i32_e32 v125, 31, v124
	v_lshlrev_b64 v[116:117], 10, v[124:125]
	v_lshl_add_u64 v[126:127], v[116:117], 0, v[148:149]
	s_and_b64 vcc, exec, s[10:11]
	v_lshl_add_u64 v[130:131], v[126:127], 2, s[20:21]
	s_cbranch_vccnz .LBB0_1297
	global_load_dwordx4 v[120:123], v[130:131], off offset:16 nt
	global_load_dwordx4 v[116:119], v[130:131], off nt
	s_mov_b64 s[4:5], 0
	s_branch .LBB0_1298

; __device__ __forceinline__ unsigned cvtpk(float lo, float hi) { f32x2_t v = {lo, hi}; bf16x2_t b = __builtin_convertvector(v, bf16x2_t); return __builtin_bit_cast(unsigned, b); }
; __device__ __forceinline__ void split_store8(bf16* hi, bf16* lo, size_t off, const F8& v) {
;     const v4u h = (v4u){cvtpk(v.a[0], v.a[1]), cvtpk(v.a[2], v.a[3]), cvtpk(v.b[0], v.b[1]), cvtpk(v.b[2], v.b[3])};
;     f32x4 ha, hb; unpack8(h, ha, hb);
;     const f32x4 ra = v.a - ha, rb = v.b - hb;
;     *(v4u*)(hi + off) = h;
;     *(v4u*)(lo + off) = (v4u){cvtpk(ra[0], ra[1]), cvtpk(ra[2], ra[3]), cvtpk(rb[0], rb[1]), cvtpk(rb[2], rb[3])};
; }
; __device__ __forceinline__ F8 split_load8(const bf16* hi, const bf16* lo, size_t off) {
;     const v4u h = *(const v4u*)(hi + off), l = *(const v4u*)(lo + off);
;     f32x4 ha, hb, la, lb; unpack8(h, ha, hb); unpack8(l, la, lb);
;     return F8{ha + la, hb + lb};
; }
;     __device__ __forceinline__ void operator()(accv (&acc)[2][2][4][2], const pg8::Unit& u, int wr, int wc, int fr, int fq) const {
;     ...
;                 const int row = rowb + 128 * ai + 16 * m; float s = 0.f;
; #pragma unroll
;                 for (int bj = 0; bj < 2; ++bj) {
;                     const size_t off = (size_t)row * D + col0 + 128 * bj;
;                     F8 bs; if (basef) { bs.a = *(const f32x4*)(basef + off); bs.b = *(const f32x4*)(basef + off + 4); } else bs = split_load8(bhi, blo, off);
;                     F8 v; v.a = bs.a + acc[ai][bj][m][0]; v.b = bs.b + acc[ai][bj][m][1];
;                     split_store8(ohi, olo, off, v);
;                     s += ((v.a[0] * v.a[0] + v.a[1] * v.a[1]) + (v.a[2] * v.a[2] + v.a[3] * v.a[3])) + ((v.b[0] * v.b[0] + v.b[1] * v.b[1]) + (v.b[2] * v.b[2] + v.b[3] * v.b[3]));
.LBB0_1298:
	v_lshlrev_b64 v[136:137], 1, v[126:127]
	s_andn2_b64 vcc, exec, s[4:5]
	v_lshl_add_u64 v[126:127], s[40:41], 0, v[136:137]
	v_lshl_add_u64 v[128:129], s[16:17], 0, v[136:137]
	s_cbranch_vccnz .LBB0_1300
	global_load_dwordx4 v[116:119], v[126:127], off nt
	global_load_dwordx4 v[120:123], v[128:129], off nt
	s_waitcnt vmcnt(1)
	v_lshlrev_b32_e32 v132, 16, v116
	v_and_b32_e32 v133, 0xffff0000, v116
	v_lshlrev_b32_e32 v116, 16, v117
	v_and_b32_e32 v117, 0xffff0000, v117
	v_lshlrev_b32_e32 v134, 16, v118
	v_and_b32_e32 v135, 0xffff0000, v118
	v_lshlrev_b32_e32 v138, 16, v119
	v_and_b32_e32 v139, 0xffff0000, v119
	s_waitcnt vmcnt(0)
	v_lshlrev_b32_e32 v152, 16, v120
	v_and_b32_e32 v153, 0xffff0000, v120
	v_lshlrev_b32_e32 v118, 16, v121
	v_and_b32_e32 v119, 0xffff0000, v121
	v_lshlrev_b32_e32 v120, 16, v122
	v_and_b32_e32 v121, 0xffff0000, v122
	v_lshlrev_b32_e32 v122, 16, v123
	v_and_b32_e32 v123, 0xffff0000, v123
	v_pk_add_f32 v[118:119], v[116:117], v[118:119]
	v_pk_add_f32 v[116:117], v[132:133], v[152:153]
	v_pk_add_f32 v[122:123], v[138:139], v[122:123]
	v_pk_add_f32 v[120:121], v[134:135], v[120:121]
.LBB0_1300:
	s_waitcnt vmcnt(0)
	v_pk_add_f32 v[132:133], v[110:111], v[118:119]
	v_pk_add_f32 v[134:135], v[108:109], v[116:117]
	v_pk_add_f32 v[122:123], v[106:107], v[122:123]
	v_pk_add_f32 v[120:121], v[104:105], v[120:121]
	v_cvt_pk_bf16_f32 v104, v134, v135
	v_cvt_pk_bf16_f32 v105, v132, v133
	v_cvt_pk_bf16_f32 v106, v120, v121
	v_cvt_pk_bf16_f32 v107, v122, v123
	v_lshlrev_b32_e32 v108, 16, v104
	v_and_b32_e32 v109, 0xffff0000, v104
	v_lshlrev_b32_e32 v110, 16, v105
	v_and_b32_e32 v111, 0xffff0000, v105
	v_lshlrev_b32_e32 v116, 16, v106
	v_and_b32_e32 v117, 0xffff0000, v106
	v_lshlrev_b32_e32 v118, 16, v107
	v_and_b32_e32 v119, 0xffff0000, v107
	v_sub_f32_e32 v111, v133, v111
	v_sub_f32_e32 v110, v132, v110
	v_sub_f32_e32 v109, v135, v109
	v_sub_f32_e32 v108, v134, v108
	v_sub_f32_e32 v138, v123, v119
	v_sub_f32_e32 v139, v122, v118
	v_sub_f32_e32 v117, v121, v117
	v_sub_f32_e32 v116, v120, v116
	v_lshl_add_u64 v[118:119], s[42:43], 0, v[136:137]
	global_store_dwordx4 v[118:119], v[104:107], off
	s_and_b64 vcc, exec, s[10:11]
	s_nop 0
	v_cvt_pk_bf16_f32 v104, v108, v109
	v_cvt_pk_bf16_f32 v105, v110, v111
	v_cvt_pk_bf16_f32 v106, v116, v117
	v_cvt_pk_bf16_f32 v107, v139, v138
	v_lshl_add_u64 v[116:117], s[44:45], 0, v[136:137]
	global_store_dwordx4 v[116:117], v[104:107], off
	s_cbranch_vccnz .LBB0_1307
	global_load_dwordx4 v[108:111], v[130:131], off offset:528 nt
	global_load_dwordx4 v[104:107], v[130:131], off offset:512 nt
	s_cbranch_execnz .LBB0_1303
.LBB0_1302:
	global_load_dwordx4 v[104:107], v[126:127], off offset:256 nt
	global_load_dwordx4 v[108:111], v[128:129], off offset:256 nt
	s_waitcnt vmcnt(1)
	v_lshlrev_b32_e32 v126, 16, v104
	v_and_b32_e32 v127, 0xffff0000, v104
	v_lshlrev_b32_e32 v104, 16, v105
	v_and_b32_e32 v105, 0xffff0000, v105
	v_lshlrev_b32_e32 v128, 16, v106
	v_and_b32_e32 v129, 0xffff0000, v106
	v_lshlrev_b32_e32 v130, 16, v107
	v_and_b32_e32 v131, 0xffff0000, v107
	s_waitcnt vmcnt(0)
	v_lshlrev_b32_e32 v136, 16, v108
	v_and_b32_e32 v137, 0xffff0000, v108
	v_lshlrev_b32_e32 v106, 16, v109
	v_and_b32_e32 v107, 0xffff0000, v109
	v_lshlrev_b32_e32 v108, 16, v110
	v_and_b32_e32 v109, 0xffff0000, v110
	v_lshlrev_b32_e32 v110, 16, v111
	v_and_b32_e32 v111, 0xffff0000, v111
	v_pk_add_f32 v[106:107], v[104:105], v[106:107]
	v_pk_add_f32 v[104:105], v[126:127], v[136:137]
	v_pk_add_f32 v[110:111], v[130:131], v[110:111]
	v_pk_add_f32 v[108:109], v[128:129], v[108:109]

;     __device__ __forceinline__ void operator()(accv (&acc)[2][2][4][2], const pg8::Unit& u, int wr, int wc, int fr, int fq) const {
;     ...
;                 const int row = rowb + 128 * ai + 16 * m; float s = 0.f;
; #pragma unroll
;                 for (int bj = 0; bj < 2; ++bj) {
;                     const size_t off = (size_t)row * D + col0 + 128 * bj;
;                     F8 bs; if (basef) { bs.a = *(const f32x4*)(basef + off); bs.b = *(const f32x4*)(basef + off + 4); } else bs = split_load8(bhi, blo, off);
.LBB0_1305:
	s_or_b64 exec, exec, s[4:5]
	v_or_b32_e32 v104, 32, v150
	v_ashrrev_i32_e32 v105, 31, v104
	v_lshlrev_b64 v[96:97], 10, v[104:105]
	v_lshl_add_u64 v[106:107], v[96:97], 0, v[148:149]
	s_and_b64 vcc, exec, s[10:11]
	v_lshl_add_u64 v[110:111], v[106:107], 2, s[20:21]
	s_cbranch_vccnz .LBB0_1308
	global_load_dwordx4 v[100:103], v[110:111], off offset:16 nt
	global_load_dwordx4 v[96:99], v[110:111], off nt
	s_mov_b64 s[4:5], 0
	s_branch .LBB0_1309

; __device__ __forceinline__ unsigned cvtpk(float lo, float hi) { f32x2_t v = {lo, hi}; bf16x2_t b = __builtin_convertvector(v, bf16x2_t); return __builtin_bit_cast(unsigned, b); }
; __device__ __forceinline__ void split_store8(bf16* hi, bf16* lo, size_t off, const F8& v) {
;     const v4u h = (v4u){cvtpk(v.a[0], v.a[1]), cvtpk(v.a[2], v.a[3]), cvtpk(v.b[0], v.b[1]), cvtpk(v.b[2], v.b[3])};
;     f32x4 ha, hb; unpack8(h, ha, hb);
;     const f32x4 ra = v.a - ha, rb = v.b - hb;
;     *(v4u*)(hi + off) = h;
;     *(v4u*)(lo + off) = (v4u){cvtpk(ra[0], ra[1]), cvtpk(ra[2], ra[3]), cvtpk(rb[0], rb[1]), cvtpk(rb[2], rb[3])};
; }
; __device__ __forceinline__ F8 split_load8(const bf16* hi, const bf16* lo, size_t off) {
;     const v4u h = *(const v4u*)(hi + off), l = *(const v4u*)(lo + off);
;     f32x4 ha, hb, la, lb; unpack8(h, ha, hb); unpack8(l, la, lb);
;     return F8{ha + la, hb + lb};
; }
;     __device__ __forceinline__ void operator()(accv (&acc)[2][2][4][2], const pg8::Unit& u, int wr, int wc, int fr, int fq) const {
;     ...
;                 const int row = rowb + 128 * ai + 16 * m; float s = 0.f;
; #pragma unroll
;                 for (int bj = 0; bj < 2; ++bj) {
;                     const size_t off = (size_t)row * D + col0 + 128 * bj;
;                     F8 bs; if (basef) { bs.a = *(const f32x4*)(basef + off); bs.b = *(const f32x4*)(basef + off + 4); } else bs = split_load8(bhi, blo, off);
;                     F8 v; v.a = bs.a + acc[ai][bj][m][0]; v.b = bs.b + acc[ai][bj][m][1];
;                     split_store8(ohi, olo, off, v);
;                     s += ((v.a[0] * v.a[0] + v.a[1] * v.a[1]) + (v.a[2] * v.a[2] + v.a[3] * v.a[3])) + ((v.b[0] * v.b[0] + v.b[1] * v.b[1]) + (v.b[2] * v.b[2] + v.b[3] * v.b[3]));
.LBB0_1309:
	v_lshlrev_b64 v[120:121], 1, v[106:107]
	s_andn2_b64 vcc, exec, s[4:5]
	v_lshl_add_u64 v[106:107], s[40:41], 0, v[120:121]
	v_lshl_add_u64 v[108:109], s[16:17], 0, v[120:121]
	s_cbranch_vccnz .LBB0_1311
	global_load_dwordx4 v[96:99], v[106:107], off nt
	global_load_dwordx4 v[100:103], v[108:109], off nt
	s_waitcnt vmcnt(1)
	v_lshlrev_b32_e32 v116, 16, v96
	v_and_b32_e32 v117, 0xffff0000, v96
	v_lshlrev_b32_e32 v96, 16, v97
	v_and_b32_e32 v97, 0xffff0000, v97
	v_lshlrev_b32_e32 v118, 16, v98
	v_and_b32_e32 v119, 0xffff0000, v98
	v_lshlrev_b32_e32 v122, 16, v99
	v_and_b32_e32 v123, 0xffff0000, v99
	s_waitcnt vmcnt(0)
	v_lshlrev_b32_e32 v124, 16, v100
	v_and_b32_e32 v125, 0xffff0000, v100
	v_lshlrev_b32_e32 v98, 16, v101
	v_and_b32_e32 v99, 0xffff0000, v101
	v_lshlrev_b32_e32 v100, 16, v102
	v_and_b32_e32 v101, 0xffff0000, v102
	v_lshlrev_b32_e32 v102, 16, v103
	v_and_b32_e32 v103, 0xffff0000, v103
	v_pk_add_f32 v[98:99], v[96:97], v[98:99]
	v_pk_add_f32 v[96:97], v[116:117], v[124:125]
	v_pk_add_f32 v[102:103], v[122:123], v[102:103]
	v_pk_add_f32 v[100:101], v[118:119], v[100:101]
.LBB0_1311:
	s_waitcnt vmcnt(0)
	v_pk_add_f32 v[116:117], v[94:95], v[98:99]
	v_pk_add_f32 v[118:119], v[92:93], v[96:97]
	v_pk_add_f32 v[102:103], v[90:91], v[102:103]
	v_pk_add_f32 v[100:101], v[88:89], v[100:101]
	v_cvt_pk_bf16_f32 v88, v118, v119
	v_cvt_pk_bf16_f32 v89, v116, v117
	v_cvt_pk_bf16_f32 v90, v100, v101
	v_cvt_pk_bf16_f32 v91, v102, v103
	v_lshlrev_b32_e32 v92, 16, v88
	v_and_b32_e32 v93, 0xffff0000, v88
	v_lshlrev_b32_e32 v94, 16, v89
	v_and_b32_e32 v95, 0xffff0000, v89
	v_lshlrev_b32_e32 v96, 16, v90
	v_and_b32_e32 v97, 0xffff0000, v90
	v_lshlrev_b32_e32 v98, 16, v91
	v_and_b32_e32 v99, 0xffff0000, v91
	v_sub_f32_e32 v95, v117, v95
	v_sub_f32_e32 v94, v116, v94
	v_sub_f32_e32 v93, v119, v93
	v_sub_f32_e32 v92, v118, v92
	v_sub_f32_e32 v122, v103, v99
	v_sub_f32_e32 v123, v102, v98
	v_sub_f32_e32 v97, v101, v97
	v_sub_f32_e32 v96, v100, v96
	v_lshl_add_u64 v[98:99], s[42:43], 0, v[120:121]
	global_store_dwordx4 v[98:99], v[88:91], off
	s_and_b64 vcc, exec, s[10:11]
	s_nop 0
	v_cvt_pk_bf16_f32 v88, v92, v93
	v_cvt_pk_bf16_f32 v89, v94, v95
	v_cvt_pk_bf16_f32 v90, v96, v97
	v_cvt_pk_bf16_f32 v91, v123, v122
	v_lshl_add_u64 v[96:97], s[44:45], 0, v[120:121]
	global_store_dwordx4 v[96:97], v[88:91], off
	s_cbranch_vccnz .LBB0_1318
	global_load_dwordx4 v[92:95], v[110:111], off offset:528 nt
	global_load_dwordx4 v[88:91], v[110:111], off offset:512 nt
	s_cbranch_execnz .LBB0_1314
.LBB0_1313:
	global_load_dwordx4 v[88:91], v[106:107], off offset:256 nt
	global_load_dwordx4 v[92:95], v[108:109], off offset:256 nt
	s_waitcnt vmcnt(1)
	v_lshlrev_b32_e32 v106, 16, v88
	v_and_b32_e32 v107, 0xffff0000, v88
	v_lshlrev_b32_e32 v88, 16, v89
	v_and_b32_e32 v89, 0xffff0000, v89
	v_lshlrev_b32_e32 v108, 16, v90
	v_and_b32_e32 v109, 0xffff0000, v90
	v_lshlrev_b32_e32 v110, 16, v91
	v_and_b32_e32 v111, 0xffff0000, v91
	s_waitcnt vmcnt(0)
	v_lshlrev_b32_e32 v120, 16, v92
	v_and_b32_e32 v121, 0xffff0000, v92
	v_lshlrev_b32_e32 v90, 16, v93
	v_and_b32_e32 v91, 0xffff0000, v93
	v_lshlrev_b32_e32 v92, 16, v94
	v_and_b32_e32 v93, 0xffff0000, v94
	v_lshlrev_b32_e32 v94, 16, v95
	v_and_b32_e32 v95, 0xffff0000, v95
	v_pk_add_f32 v[90:91], v[88:89], v[90:91]
	v_pk_add_f32 v[88:89], v[106:107], v[120:121]
	v_pk_add_f32 v[94:95], v[110:111], v[94:95]
	v_pk_add_f32 v[92:93], v[108:109], v[92:93]

;     __device__ __forceinline__ void operator()(accv (&acc)[2][2][4][2], const pg8::Unit& u, int wr, int wc, int fr, int fq) const {
;     ...
;                 const int row = rowb + 128 * ai + 16 * m; float s = 0.f;
; #pragma unroll
;                 for (int bj = 0; bj < 2; ++bj) {
;                     const size_t off = (size_t)row * D + col0 + 128 * bj;
;                     F8 bs; if (basef) { bs.a = *(const f32x4*)(basef + off); bs.b = *(const f32x4*)(basef + off + 4); } else bs = split_load8(bhi, blo, off);
.LBB0_1316:
	s_or_b64 exec, exec, s[4:5]
	v_or_b32_e32 v88, 48, v150
	v_ashrrev_i32_e32 v89, 31, v88
	v_lshlrev_b64 v[80:81], 10, v[88:89]
	v_lshl_add_u64 v[90:91], v[80:81], 0, v[148:149]
	s_and_b64 vcc, exec, s[10:11]
	v_lshl_add_u64 v[94:95], v[90:91], 2, s[20:21]
	s_cbranch_vccnz .LBB0_1319
	global_load_dwordx4 v[84:87], v[94:95], off offset:16 nt
	global_load_dwordx4 v[80:83], v[94:95], off nt
	s_mov_b64 s[4:5], 0
	s_branch .LBB0_1320

; __device__ __forceinline__ unsigned cvtpk(float lo, float hi) { f32x2_t v = {lo, hi}; bf16x2_t b = __builtin_convertvector(v, bf16x2_t); return __builtin_bit_cast(unsigned, b); }
; __device__ __forceinline__ void split_store8(bf16* hi, bf16* lo, size_t off, const F8& v) {
;     const v4u h = (v4u){cvtpk(v.a[0], v.a[1]), cvtpk(v.a[2], v.a[3]), cvtpk(v.b[0], v.b[1]), cvtpk(v.b[2], v.b[3])};
;     f32x4 ha, hb; unpack8(h, ha, hb);
;     const f32x4 ra = v.a - ha, rb = v.b - hb;
;     *(v4u*)(hi + off) = h;
;     *(v4u*)(lo + off) = (v4u){cvtpk(ra[0], ra[1]), cvtpk(ra[2], ra[3]), cvtpk(rb[0], rb[1]), cvtpk(rb[2], rb[3])};
; }
; __device__ __forceinline__ F8 split_load8(const bf16* hi, const bf16* lo, size_t off) {
;     const v4u h = *(const v4u*)(hi + off), l = *(const v4u*)(lo + off);
;     f32x4 ha, hb, la, lb; unpack8(h, ha, hb); unpack8(l, la, lb);
;     return F8{ha + la, hb + lb};
; }
;     __device__ __forceinline__ void operator()(accv (&acc)[2][2][4][2], const pg8::Unit& u, int wr, int wc, int fr, int fq) const {
;     ...
;                 const int row = rowb + 128 * ai + 16 * m; float s = 0.f;
; #pragma unroll
;                 for (int bj = 0; bj < 2; ++bj) {
;                     const size_t off = (size_t)row * D + col0 + 128 * bj;
;                     F8 bs; if (basef) { bs.a = *(const f32x4*)(basef + off); bs.b = *(const f32x4*)(basef + off + 4); } else bs = split_load8(bhi, blo, off);
;                     F8 v; v.a = bs.a + acc[ai][bj][m][0]; v.b = bs.b + acc[ai][bj][m][1];
;                     split_store8(ohi, olo, off, v);
;                     s += ((v.a[0] * v.a[0] + v.a[1] * v.a[1]) + (v.a[2] * v.a[2] + v.a[3] * v.a[3])) + ((v.b[0] * v.b[0] + v.b[1] * v.b[1]) + (v.b[2] * v.b[2] + v.b[3] * v.b[3]));
.LBB0_1320:
	v_lshlrev_b64 v[100:101], 1, v[90:91]
	s_andn2_b64 vcc, exec, s[4:5]
	v_lshl_add_u64 v[90:91], s[40:41], 0, v[100:101]
	v_lshl_add_u64 v[92:93], s[16:17], 0, v[100:101]
	s_cbranch_vccnz .LBB0_1322
	global_load_dwordx4 v[80:83], v[90:91], off nt
	global_load_dwordx4 v[84:87], v[92:93], off nt
	s_waitcnt vmcnt(1)
	v_lshlrev_b32_e32 v96, 16, v80
	v_and_b32_e32 v97, 0xffff0000, v80
	v_lshlrev_b32_e32 v80, 16, v81
	v_and_b32_e32 v81, 0xffff0000, v81
	v_lshlrev_b32_e32 v98, 16, v82
	v_and_b32_e32 v99, 0xffff0000, v82
	v_lshlrev_b32_e32 v102, 16, v83
	v_and_b32_e32 v103, 0xffff0000, v83
	s_waitcnt vmcnt(0)
	v_lshlrev_b32_e32 v104, 16, v84
	v_and_b32_e32 v105, 0xffff0000, v84
	v_lshlrev_b32_e32 v82, 16, v85
	v_and_b32_e32 v83, 0xffff0000, v85
	v_lshlrev_b32_e32 v84, 16, v86
	v_and_b32_e32 v85, 0xffff0000, v86
	v_lshlrev_b32_e32 v86, 16, v87
	v_and_b32_e32 v87, 0xffff0000, v87
	v_pk_add_f32 v[82:83], v[80:81], v[82:83]
	v_pk_add_f32 v[80:81], v[96:97], v[104:105]
	v_pk_add_f32 v[86:87], v[102:103], v[86:87]
	v_pk_add_f32 v[84:85], v[98:99], v[84:85]
.LBB0_1322:
	s_waitcnt vmcnt(0)
	v_pk_add_f32 v[96:97], v[78:79], v[82:83]
	v_pk_add_f32 v[98:99], v[76:77], v[80:81]
	v_pk_add_f32 v[86:87], v[74:75], v[86:87]
	v_pk_add_f32 v[84:85], v[72:73], v[84:85]
	v_cvt_pk_bf16_f32 v72, v98, v99
	v_cvt_pk_bf16_f32 v73, v96, v97
	v_cvt_pk_bf16_f32 v74, v84, v85
	v_cvt_pk_bf16_f32 v75, v86, v87
	v_lshlrev_b32_e32 v76, 16, v72
	v_and_b32_e32 v77, 0xffff0000, v72
	v_lshlrev_b32_e32 v78, 16, v73
	v_and_b32_e32 v79, 0xffff0000, v73
	v_lshlrev_b32_e32 v80, 16, v74
	v_and_b32_e32 v81, 0xffff0000, v74
	v_lshlrev_b32_e32 v82, 16, v75
	v_and_b32_e32 v83, 0xffff0000, v75
	v_sub_f32_e32 v79, v97, v79
	v_sub_f32_e32 v78, v96, v78
	v_sub_f32_e32 v77, v99, v77
	v_sub_f32_e32 v76, v98, v76
	v_sub_f32_e32 v102, v87, v83
	v_sub_f32_e32 v103, v86, v82
	v_sub_f32_e32 v81, v85, v81
	v_sub_f32_e32 v80, v84, v80
	v_lshl_add_u64 v[82:83], s[42:43], 0, v[100:101]
	global_store_dwordx4 v[82:83], v[72:75], off
	s_and_b64 vcc, exec, s[10:11]
	s_nop 0
	v_cvt_pk_bf16_f32 v72, v76, v77
	v_cvt_pk_bf16_f32 v73, v78, v79
	v_cvt_pk_bf16_f32 v74, v80, v81
	v_cvt_pk_bf16_f32 v75, v103, v102
	v_lshl_add_u64 v[80:81], s[44:45], 0, v[100:101]
	global_store_dwordx4 v[80:81], v[72:75], off
	s_cbranch_vccnz .LBB0_1329
	global_load_dwordx4 v[76:79], v[94:95], off offset:528 nt
	global_load_dwordx4 v[72:75], v[94:95], off offset:512 nt
	s_cbranch_execnz .LBB0_1325
.LBB0_1324:
	global_load_dwordx4 v[72:75], v[90:91], off offset:256 nt
	global_load_dwordx4 v[76:79], v[92:93], off offset:256 nt
	s_waitcnt vmcnt(1)
	v_lshlrev_b32_e32 v90, 16, v72
	v_and_b32_e32 v91, 0xffff0000, v72
	v_lshlrev_b32_e32 v72, 16, v73
	v_and_b32_e32 v73, 0xffff0000, v73
	v_lshlrev_b32_e32 v92, 16, v74
	v_and_b32_e32 v93, 0xffff0000, v74
	v_lshlrev_b32_e32 v94, 16, v75
	v_and_b32_e32 v95, 0xffff0000, v75
	s_waitcnt vmcnt(0)
	v_lshlrev_b32_e32 v100, 16, v76
	v_and_b32_e32 v101, 0xffff0000, v76
	v_lshlrev_b32_e32 v74, 16, v77
	v_and_b32_e32 v75, 0xffff0000, v77
	v_lshlrev_b32_e32 v76, 16, v78
	v_and_b32_e32 v77, 0xffff0000, v78
	v_lshlrev_b32_e32 v78, 16, v79
	v_and_b32_e32 v79, 0xffff0000, v79
	v_pk_add_f32 v[74:75], v[72:73], v[74:75]
	v_pk_add_f32 v[72:73], v[90:91], v[100:101]
	v_pk_add_f32 v[78:79], v[94:95], v[78:79]
	v_pk_add_f32 v[76:77], v[92:93], v[76:77]

;     __device__ __forceinline__ void operator()(accv (&acc)[2][2][4][2], const pg8::Unit& u, int wr, int wc, int fr, int fq) const {
;     ...
;                 const int row = rowb + 128 * ai + 16 * m; float s = 0.f;
; #pragma unroll
;                 for (int bj = 0; bj < 2; ++bj) {
;                     const size_t off = (size_t)row * D + col0 + 128 * bj;
;                     F8 bs; if (basef) { bs.a = *(const f32x4*)(basef + off); bs.b = *(const f32x4*)(basef + off + 4); } else bs = split_load8(bhi, blo, off);
.LBB0_1327:
	s_or_b64 exec, exec, s[4:5]
	v_add_u32_e32 v72, 0x80, v150
	v_ashrrev_i32_e32 v73, 31, v72
	v_lshlrev_b64 v[64:65], 10, v[72:73]
	v_lshl_add_u64 v[74:75], v[64:65], 0, v[148:149]
	s_and_b64 vcc, exec, s[10:11]
	v_lshl_add_u64 v[78:79], v[74:75], 2, s[20:21]
	s_cbranch_vccnz .LBB0_1330
	global_load_dwordx4 v[68:71], v[78:79], off offset:16 nt
	global_load_dwordx4 v[64:67], v[78:79], off nt
	s_mov_b64 s[4:5], 0
	s_branch .LBB0_1331

; __device__ __forceinline__ unsigned cvtpk(float lo, float hi) { f32x2_t v = {lo, hi}; bf16x2_t b = __builtin_convertvector(v, bf16x2_t); return __builtin_bit_cast(unsigned, b); }
; __device__ __forceinline__ void split_store8(bf16* hi, bf16* lo, size_t off, const F8& v) {
;     const v4u h = (v4u){cvtpk(v.a[0], v.a[1]), cvtpk(v.a[2], v.a[3]), cvtpk(v.b[0], v.b[1]), cvtpk(v.b[2], v.b[3])};
;     f32x4 ha, hb; unpack8(h, ha, hb);
;     const f32x4 ra = v.a - ha, rb = v.b - hb;
;     *(v4u*)(hi + off) = h;
;     *(v4u*)(lo + off) = (v4u){cvtpk(ra[0], ra[1]), cvtpk(ra[2], ra[3]), cvtpk(rb[0], rb[1]), cvtpk(rb[2], rb[3])};
; }
; __device__ __forceinline__ F8 split_load8(const bf16* hi, const bf16* lo, size_t off) {
;     const v4u h = *(const v4u*)(hi + off), l = *(const v4u*)(lo + off);
;     f32x4 ha, hb, la, lb; unpack8(h, ha, hb); unpack8(l, la, lb);
;     return F8{ha + la, hb + lb};
; }
;     __device__ __forceinline__ void operator()(accv (&acc)[2][2][4][2], const pg8::Unit& u, int wr, int wc, int fr, int fq) const {
;     ...
;                 const int row = rowb + 128 * ai + 16 * m; float s = 0.f;
; #pragma unroll
;                 for (int bj = 0; bj < 2; ++bj) {
;                     const size_t off = (size_t)row * D + col0 + 128 * bj;
;                     F8 bs; if (basef) { bs.a = *(const f32x4*)(basef + off); bs.b = *(const f32x4*)(basef + off + 4); } else bs = split_load8(bhi, blo, off);
;                     F8 v; v.a = bs.a + acc[ai][bj][m][0]; v.b = bs.b + acc[ai][bj][m][1];
;                     split_store8(ohi, olo, off, v);
;                     s += ((v.a[0] * v.a[0] + v.a[1] * v.a[1]) + (v.a[2] * v.a[2] + v.a[3] * v.a[3])) + ((v.b[0] * v.b[0] + v.b[1] * v.b[1]) + (v.b[2] * v.b[2] + v.b[3] * v.b[3]));
.LBB0_1331:
	v_lshlrev_b64 v[84:85], 1, v[74:75]
	s_andn2_b64 vcc, exec, s[4:5]
	v_lshl_add_u64 v[74:75], s[40:41], 0, v[84:85]
	v_lshl_add_u64 v[76:77], s[16:17], 0, v[84:85]
	s_cbranch_vccnz .LBB0_1333
	global_load_dwordx4 v[64:67], v[74:75], off nt
	global_load_dwordx4 v[68:71], v[76:77], off nt
	s_waitcnt vmcnt(1)
	v_lshlrev_b32_e32 v80, 16, v64
	v_and_b32_e32 v81, 0xffff0000, v64
	v_lshlrev_b32_e32 v64, 16, v65
	v_and_b32_e32 v65, 0xffff0000, v65
	v_lshlrev_b32_e32 v82, 16, v66
	v_and_b32_e32 v83, 0xffff0000, v66
	v_lshlrev_b32_e32 v86, 16, v67
	v_and_b32_e32 v87, 0xffff0000, v67
	s_waitcnt vmcnt(0)
	v_lshlrev_b32_e32 v88, 16, v68
	v_and_b32_e32 v89, 0xffff0000, v68
	v_lshlrev_b32_e32 v66, 16, v69
	v_and_b32_e32 v67, 0xffff0000, v69
	v_lshlrev_b32_e32 v68, 16, v70
	v_and_b32_e32 v69, 0xffff0000, v70
	v_lshlrev_b32_e32 v70, 16, v71
	v_and_b32_e32 v71, 0xffff0000, v71
	v_pk_add_f32 v[66:67], v[64:65], v[66:67]
	v_pk_add_f32 v[64:65], v[80:81], v[88:89]
	v_pk_add_f32 v[70:71], v[86:87], v[70:71]
	v_pk_add_f32 v[68:69], v[82:83], v[68:69]
.LBB0_1333:
	s_waitcnt vmcnt(0)
	v_pk_add_f32 v[80:81], v[62:63], v[66:67]
	v_pk_add_f32 v[82:83], v[60:61], v[64:65]
	v_pk_add_f32 v[70:71], v[58:59], v[70:71]
	v_pk_add_f32 v[68:69], v[56:57], v[68:69]
	v_cvt_pk_bf16_f32 v56, v82, v83
	v_cvt_pk_bf16_f32 v57, v80, v81
	v_cvt_pk_bf16_f32 v58, v68, v69
	v_cvt_pk_bf16_f32 v59, v70, v71
	v_lshlrev_b32_e32 v60, 16, v56
	v_and_b32_e32 v61, 0xffff0000, v56
	v_lshlrev_b32_e32 v62, 16, v57
	v_and_b32_e32 v63, 0xffff0000, v57
	v_lshlrev_b32_e32 v64, 16, v58
	v_and_b32_e32 v65, 0xffff0000, v58
	v_lshlrev_b32_e32 v66, 16, v59
	v_and_b32_e32 v67, 0xffff0000, v59
	v_sub_f32_e32 v63, v81, v63
	v_sub_f32_e32 v62, v80, v62
	v_sub_f32_e32 v61, v83, v61
	v_sub_f32_e32 v60, v82, v60
	v_sub_f32_e32 v86, v71, v67
	v_sub_f32_e32 v87, v70, v66
	v_sub_f32_e32 v65, v69, v65
	v_sub_f32_e32 v64, v68, v64
	v_lshl_add_u64 v[66:67], s[42:43], 0, v[84:85]
	global_store_dwordx4 v[66:67], v[56:59], off
	s_and_b64 vcc, exec, s[10:11]
	s_nop 0
	v_cvt_pk_bf16_f32 v56, v60, v61
	v_cvt_pk_bf16_f32 v57, v62, v63
	v_cvt_pk_bf16_f32 v58, v64, v65
	v_cvt_pk_bf16_f32 v59, v87, v86
	v_lshl_add_u64 v[64:65], s[44:45], 0, v[84:85]
	global_store_dwordx4 v[64:65], v[56:59], off
	s_cbranch_vccnz .LBB0_1340
	global_load_dwordx4 v[60:63], v[78:79], off offset:528 nt
	global_load_dwordx4 v[56:59], v[78:79], off offset:512 nt
	s_cbranch_execnz .LBB0_1336
.LBB0_1335:
	global_load_dwordx4 v[56:59], v[74:75], off offset:256 nt
	global_load_dwordx4 v[60:63], v[76:77], off offset:256 nt
	s_waitcnt vmcnt(1)
	v_lshlrev_b32_e32 v74, 16, v56
	v_and_b32_e32 v75, 0xffff0000, v56
	v_lshlrev_b32_e32 v56, 16, v57
	v_and_b32_e32 v57, 0xffff0000, v57
	v_lshlrev_b32_e32 v76, 16, v58
	v_and_b32_e32 v77, 0xffff0000, v58
	v_lshlrev_b32_e32 v78, 16, v59
	v_and_b32_e32 v79, 0xffff0000, v59
	s_waitcnt vmcnt(0)
	v_lshlrev_b32_e32 v84, 16, v60
	v_and_b32_e32 v85, 0xffff0000, v60
	v_lshlrev_b32_e32 v58, 16, v61
	v_and_b32_e32 v59, 0xffff0000, v61
	v_lshlrev_b32_e32 v60, 16, v62
	v_and_b32_e32 v61, 0xffff0000, v62
	v_lshlrev_b32_e32 v62, 16, v63
	v_and_b32_e32 v63, 0xffff0000, v63
	v_pk_add_f32 v[58:59], v[56:57], v[58:59]
	v_pk_add_f32 v[56:57], v[74:75], v[84:85]
	v_pk_add_f32 v[62:63], v[78:79], v[62:63]
	v_pk_add_f32 v[60:61], v[76:77], v[60:61]

;     __device__ __forceinline__ void operator()(accv (&acc)[2][2][4][2], const pg8::Unit& u, int wr, int wc, int fr, int fq) const {
;     ...
;                 const int row = rowb + 128 * ai + 16 * m; float s = 0.f;
; #pragma unroll
;                 for (int bj = 0; bj < 2; ++bj) {
;                     const size_t off = (size_t)row * D + col0 + 128 * bj;
;                     F8 bs; if (basef) { bs.a = *(const f32x4*)(basef + off); bs.b = *(const f32x4*)(basef + off + 4); } else bs = split_load8(bhi, blo, off);
.LBB0_1338:
	s_or_b64 exec, exec, s[4:5]
	v_add_u32_e32 v56, 0x90, v150
	v_ashrrev_i32_e32 v57, 31, v56
	v_lshlrev_b64 v[48:49], 10, v[56:57]
	v_lshl_add_u64 v[58:59], v[48:49], 0, v[148:149]
	s_and_b64 vcc, exec, s[10:11]
	v_lshl_add_u64 v[62:63], v[58:59], 2, s[20:21]
	s_cbranch_vccnz .LBB0_1341
	global_load_dwordx4 v[52:55], v[62:63], off offset:16 nt
	global_load_dwordx4 v[48:51], v[62:63], off nt
	s_mov_b64 s[4:5], 0
	s_branch .LBB0_1342

; __device__ __forceinline__ unsigned cvtpk(float lo, float hi) { f32x2_t v = {lo, hi}; bf16x2_t b = __builtin_convertvector(v, bf16x2_t); return __builtin_bit_cast(unsigned, b); }
; __device__ __forceinline__ void split_store8(bf16* hi, bf16* lo, size_t off, const F8& v) {
;     const v4u h = (v4u){cvtpk(v.a[0], v.a[1]), cvtpk(v.a[2], v.a[3]), cvtpk(v.b[0], v.b[1]), cvtpk(v.b[2], v.b[3])};
;     f32x4 ha, hb; unpack8(h, ha, hb);
;     const f32x4 ra = v.a - ha, rb = v.b - hb;
;     *(v4u*)(hi + off) = h;
;     *(v4u*)(lo + off) = (v4u){cvtpk(ra[0], ra[1]), cvtpk(ra[2], ra[3]), cvtpk(rb[0], rb[1]), cvtpk(rb[2], rb[3])};
; }
; __device__ __forceinline__ F8 split_load8(const bf16* hi, const bf16* lo, size_t off) {
;     const v4u h = *(const v4u*)(hi + off), l = *(const v4u*)(lo + off);
;     f32x4 ha, hb, la, lb; unpack8(h, ha, hb); unpack8(l, la, lb);
;     return F8{ha + la, hb + lb};
; }
;     __device__ __forceinline__ void operator()(accv (&acc)[2][2][4][2], const pg8::Unit& u, int wr, int wc, int fr, int fq) const {
;     ...
;                 const int row = rowb + 128 * ai + 16 * m; float s = 0.f;
; #pragma unroll
;                 for (int bj = 0; bj < 2; ++bj) {
;                     const size_t off = (size_t)row * D + col0 + 128 * bj;
;                     F8 bs; if (basef) { bs.a = *(const f32x4*)(basef + off); bs.b = *(const f32x4*)(basef + off + 4); } else bs = split_load8(bhi, blo, off);
;                     F8 v; v.a = bs.a + acc[ai][bj][m][0]; v.b = bs.b + acc[ai][bj][m][1];
;                     split_store8(ohi, olo, off, v);
;                     s += ((v.a[0] * v.a[0] + v.a[1] * v.a[1]) + (v.a[2] * v.a[2] + v.a[3] * v.a[3])) + ((v.b[0] * v.b[0] + v.b[1] * v.b[1]) + (v.b[2] * v.b[2] + v.b[3] * v.b[3]));
.LBB0_1342:
	v_lshlrev_b64 v[68:69], 1, v[58:59]
	s_andn2_b64 vcc, exec, s[4:5]
	v_lshl_add_u64 v[58:59], s[40:41], 0, v[68:69]
	v_lshl_add_u64 v[60:61], s[16:17], 0, v[68:69]
	s_cbranch_vccnz .LBB0_1344
	global_load_dwordx4 v[48:51], v[58:59], off nt
	global_load_dwordx4 v[52:55], v[60:61], off nt
	s_waitcnt vmcnt(1)
	v_lshlrev_b32_e32 v64, 16, v48
	v_and_b32_e32 v65, 0xffff0000, v48
	v_lshlrev_b32_e32 v48, 16, v49
	v_and_b32_e32 v49, 0xffff0000, v49
	v_lshlrev_b32_e32 v66, 16, v50
	v_and_b32_e32 v67, 0xffff0000, v50
	v_lshlrev_b32_e32 v70, 16, v51
	v_and_b32_e32 v71, 0xffff0000, v51
	s_waitcnt vmcnt(0)
	v_lshlrev_b32_e32 v72, 16, v52
	v_and_b32_e32 v73, 0xffff0000, v52
	v_lshlrev_b32_e32 v50, 16, v53
	v_and_b32_e32 v51, 0xffff0000, v53
	v_lshlrev_b32_e32 v52, 16, v54
	v_and_b32_e32 v53, 0xffff0000, v54
	v_lshlrev_b32_e32 v54, 16, v55
	v_and_b32_e32 v55, 0xffff0000, v55
	v_pk_add_f32 v[50:51], v[48:49], v[50:51]
	v_pk_add_f32 v[48:49], v[64:65], v[72:73]
	v_pk_add_f32 v[54:55], v[70:71], v[54:55]
	v_pk_add_f32 v[52:53], v[66:67], v[52:53]
.LBB0_1344:
	s_waitcnt vmcnt(0)
	v_pk_add_f32 v[64:65], v[46:47], v[50:51]
	v_pk_add_f32 v[66:67], v[44:45], v[48:49]
	v_pk_add_f32 v[54:55], v[42:43], v[54:55]
	v_pk_add_f32 v[52:53], v[40:41], v[52:53]
	v_cvt_pk_bf16_f32 v40, v66, v67
	v_cvt_pk_bf16_f32 v41, v64, v65
	v_cvt_pk_bf16_f32 v42, v52, v53
	v_cvt_pk_bf16_f32 v43, v54, v55
	v_lshlrev_b32_e32 v44, 16, v40
	v_and_b32_e32 v45, 0xffff0000, v40
	v_lshlrev_b32_e32 v46, 16, v41
	v_and_b32_e32 v47, 0xffff0000, v41
	v_lshlrev_b32_e32 v48, 16, v42
	v_and_b32_e32 v49, 0xffff0000, v42
	v_lshlrev_b32_e32 v50, 16, v43
	v_and_b32_e32 v51, 0xffff0000, v43
	v_sub_f32_e32 v47, v65, v47
	v_sub_f32_e32 v46, v64, v46
	v_sub_f32_e32 v45, v67, v45
	v_sub_f32_e32 v44, v66, v44
	v_sub_f32_e32 v70, v55, v51
	v_sub_f32_e32 v71, v54, v50
	v_sub_f32_e32 v49, v53, v49
	v_sub_f32_e32 v48, v52, v48
	v_lshl_add_u64 v[50:51], s[42:43], 0, v[68:69]
	global_store_dwordx4 v[50:51], v[40:43], off
	s_and_b64 vcc, exec, s[10:11]
	s_nop 0
	v_cvt_pk_bf16_f32 v40, v44, v45
	v_cvt_pk_bf16_f32 v41, v46, v47
	v_cvt_pk_bf16_f32 v42, v48, v49
	v_cvt_pk_bf16_f32 v43, v71, v70
	v_lshl_add_u64 v[48:49], s[44:45], 0, v[68:69]
	global_store_dwordx4 v[48:49], v[40:43], off
	s_cbranch_vccnz .LBB0_1351
	global_load_dwordx4 v[44:47], v[62:63], off offset:528 nt
	global_load_dwordx4 v[40:43], v[62:63], off offset:512 nt
	s_cbranch_execnz .LBB0_1347
.LBB0_1346:
	global_load_dwordx4 v[40:43], v[58:59], off offset:256 nt
	global_load_dwordx4 v[44:47], v[60:61], off offset:256 nt
	s_waitcnt vmcnt(1)
	v_lshlrev_b32_e32 v58, 16, v40
	v_and_b32_e32 v59, 0xffff0000, v40
	v_lshlrev_b32_e32 v40, 16, v41
	v_and_b32_e32 v41, 0xffff0000, v41
	v_lshlrev_b32_e32 v60, 16, v42
	v_and_b32_e32 v61, 0xffff0000, v42
	v_lshlrev_b32_e32 v62, 16, v43
	v_and_b32_e32 v63, 0xffff0000, v43
	s_waitcnt vmcnt(0)
	v_lshlrev_b32_e32 v68, 16, v44
	v_and_b32_e32 v69, 0xffff0000, v44
	v_lshlrev_b32_e32 v42, 16, v45
	v_and_b32_e32 v43, 0xffff0000, v45
	v_lshlrev_b32_e32 v44, 16, v46
	v_and_b32_e32 v45, 0xffff0000, v46
	v_lshlrev_b32_e32 v46, 16, v47
	v_and_b32_e32 v47, 0xffff0000, v47
	v_pk_add_f32 v[42:43], v[40:41], v[42:43]
	v_pk_add_f32 v[40:41], v[58:59], v[68:69]
	v_pk_add_f32 v[46:47], v[62:63], v[46:47]
	v_pk_add_f32 v[44:45], v[60:61], v[44:45]

;     __device__ __forceinline__ void operator()(accv (&acc)[2][2][4][2], const pg8::Unit& u, int wr, int wc, int fr, int fq) const {
;     ...
;                 const int row = rowb + 128 * ai + 16 * m; float s = 0.f;
; #pragma unroll
;                 for (int bj = 0; bj < 2; ++bj) {
;                     const size_t off = (size_t)row * D + col0 + 128 * bj;
;                     F8 bs; if (basef) { bs.a = *(const f32x4*)(basef + off); bs.b = *(const f32x4*)(basef + off + 4); } else bs = split_load8(bhi, blo, off);
.LBB0_1349:
	s_or_b64 exec, exec, s[4:5]
	v_add_u32_e32 v40, 0xa0, v150
	v_ashrrev_i32_e32 v41, 31, v40
	v_lshlrev_b64 v[32:33], 10, v[40:41]
	v_lshl_add_u64 v[42:43], v[32:33], 0, v[148:149]
	s_and_b64 vcc, exec, s[10:11]
	v_lshl_add_u64 v[46:47], v[42:43], 2, s[20:21]
	s_cbranch_vccnz .LBB0_1352
	global_load_dwordx4 v[36:39], v[46:47], off offset:16 nt
	global_load_dwordx4 v[32:35], v[46:47], off nt
	s_mov_b64 s[4:5], 0
	s_branch .LBB0_1353

; __device__ __forceinline__ unsigned cvtpk(float lo, float hi) { f32x2_t v = {lo, hi}; bf16x2_t b = __builtin_convertvector(v, bf16x2_t); return __builtin_bit_cast(unsigned, b); }
; __device__ __forceinline__ void split_store8(bf16* hi, bf16* lo, size_t off, const F8& v) {
;     const v4u h = (v4u){cvtpk(v.a[0], v.a[1]), cvtpk(v.a[2], v.a[3]), cvtpk(v.b[0], v.b[1]), cvtpk(v.b[2], v.b[3])};
;     f32x4 ha, hb; unpack8(h, ha, hb);
;     const f32x4 ra = v.a - ha, rb = v.b - hb;
;     *(v4u*)(hi + off) = h;
;     *(v4u*)(lo + off) = (v4u){cvtpk(ra[0], ra[1]), cvtpk(ra[2], ra[3]), cvtpk(rb[0], rb[1]), cvtpk(rb[2], rb[3])};
; }
; __device__ __forceinline__ F8 split_load8(const bf16* hi, const bf16* lo, size_t off) {
;     const v4u h = *(const v4u*)(hi + off), l = *(const v4u*)(lo + off);
;     f32x4 ha, hb, la, lb; unpack8(h, ha, hb); unpack8(l, la, lb);
;     return F8{ha + la, hb + lb};
; }
;     __device__ __forceinline__ void operator()(accv (&acc)[2][2][4][2], const pg8::Unit& u, int wr, int wc, int fr, int fq) const {
;     ...
;                 const int row = rowb + 128 * ai + 16 * m; float s = 0.f;
; #pragma unroll
;                 for (int bj = 0; bj < 2; ++bj) {
;                     const size_t off = (size_t)row * D + col0 + 128 * bj;
;                     F8 bs; if (basef) { bs.a = *(const f32x4*)(basef + off); bs.b = *(const f32x4*)(basef + off + 4); } else bs = split_load8(bhi, blo, off);
;                     F8 v; v.a = bs.a + acc[ai][bj][m][0]; v.b = bs.b + acc[ai][bj][m][1];
;                     split_store8(ohi, olo, off, v);
;                     s += ((v.a[0] * v.a[0] + v.a[1] * v.a[1]) + (v.a[2] * v.a[2] + v.a[3] * v.a[3])) + ((v.b[0] * v.b[0] + v.b[1] * v.b[1]) + (v.b[2] * v.b[2] + v.b[3] * v.b[3]));
.LBB0_1353:
	v_lshlrev_b64 v[52:53], 1, v[42:43]
	s_andn2_b64 vcc, exec, s[4:5]
	v_lshl_add_u64 v[42:43], s[40:41], 0, v[52:53]
	v_lshl_add_u64 v[44:45], s[16:17], 0, v[52:53]
	s_cbranch_vccnz .LBB0_1355
	global_load_dwordx4 v[32:35], v[42:43], off nt
	global_load_dwordx4 v[36:39], v[44:45], off nt
	s_waitcnt vmcnt(1)
	v_lshlrev_b32_e32 v48, 16, v32
	v_and_b32_e32 v49, 0xffff0000, v32
	v_lshlrev_b32_e32 v32, 16, v33
	v_and_b32_e32 v33, 0xffff0000, v33
	v_lshlrev_b32_e32 v50, 16, v34
	v_and_b32_e32 v51, 0xffff0000, v34
	v_lshlrev_b32_e32 v54, 16, v35
	v_and_b32_e32 v55, 0xffff0000, v35
	s_waitcnt vmcnt(0)
	v_lshlrev_b32_e32 v56, 16, v36
	v_and_b32_e32 v57, 0xffff0000, v36
	v_lshlrev_b32_e32 v34, 16, v37
	v_and_b32_e32 v35, 0xffff0000, v37
	v_lshlrev_b32_e32 v36, 16, v38
	v_and_b32_e32 v37, 0xffff0000, v38
	v_lshlrev_b32_e32 v38, 16, v39
	v_and_b32_e32 v39, 0xffff0000, v39
	v_pk_add_f32 v[34:35], v[32:33], v[34:35]
	v_pk_add_f32 v[32:33], v[48:49], v[56:57]
	v_pk_add_f32 v[38:39], v[54:55], v[38:39]
	v_pk_add_f32 v[36:37], v[50:51], v[36:37]
.LBB0_1355:
	s_waitcnt vmcnt(0)
	v_pk_add_f32 v[48:49], v[30:31], v[34:35]
	v_pk_add_f32 v[50:51], v[28:29], v[32:33]
	v_pk_add_f32 v[38:39], v[26:27], v[38:39]
	v_pk_add_f32 v[36:37], v[24:25], v[36:37]
	v_cvt_pk_bf16_f32 v24, v50, v51
	v_cvt_pk_bf16_f32 v25, v48, v49
	v_cvt_pk_bf16_f32 v26, v36, v37
	v_cvt_pk_bf16_f32 v27, v38, v39
	v_lshlrev_b32_e32 v28, 16, v24
	v_and_b32_e32 v29, 0xffff0000, v24
	v_lshlrev_b32_e32 v30, 16, v25
	v_and_b32_e32 v31, 0xffff0000, v25
	v_lshlrev_b32_e32 v32, 16, v26
	v_and_b32_e32 v33, 0xffff0000, v26
	v_lshlrev_b32_e32 v34, 16, v27
	v_and_b32_e32 v35, 0xffff0000, v27
	v_sub_f32_e32 v31, v49, v31
	v_sub_f32_e32 v30, v48, v30
	v_sub_f32_e32 v29, v51, v29
	v_sub_f32_e32 v28, v50, v28
	v_sub_f32_e32 v54, v39, v35
	v_sub_f32_e32 v55, v38, v34
	v_sub_f32_e32 v33, v37, v33
	v_sub_f32_e32 v32, v36, v32
	v_lshl_add_u64 v[34:35], s[42:43], 0, v[52:53]
	global_store_dwordx4 v[34:35], v[24:27], off
	s_and_b64 vcc, exec, s[10:11]
	s_nop 0
	v_cvt_pk_bf16_f32 v24, v28, v29
	v_cvt_pk_bf16_f32 v25, v30, v31
	v_cvt_pk_bf16_f32 v26, v32, v33
	v_cvt_pk_bf16_f32 v27, v55, v54
	v_lshl_add_u64 v[32:33], s[44:45], 0, v[52:53]
	global_store_dwordx4 v[32:33], v[24:27], off
	s_cbranch_vccnz .LBB0_1362
	global_load_dwordx4 v[28:31], v[46:47], off offset:528 nt
	global_load_dwordx4 v[24:27], v[46:47], off offset:512 nt
	s_cbranch_execnz .LBB0_1358
.LBB0_1357:
	global_load_dwordx4 v[24:27], v[42:43], off offset:256 nt
	global_load_dwordx4 v[28:31], v[44:45], off offset:256 nt
	s_waitcnt vmcnt(1)
	v_lshlrev_b32_e32 v42, 16, v24
	v_and_b32_e32 v43, 0xffff0000, v24
	v_lshlrev_b32_e32 v24, 16, v25
	v_and_b32_e32 v25, 0xffff0000, v25
	v_lshlrev_b32_e32 v44, 16, v26
	v_and_b32_e32 v45, 0xffff0000, v26
	v_lshlrev_b32_e32 v46, 16, v27
	v_and_b32_e32 v47, 0xffff0000, v27
	s_waitcnt vmcnt(0)
	v_lshlrev_b32_e32 v52, 16, v28
	v_and_b32_e32 v53, 0xffff0000, v28
	v_lshlrev_b32_e32 v26, 16, v29
	v_and_b32_e32 v27, 0xffff0000, v29
	v_lshlrev_b32_e32 v28, 16, v30
	v_and_b32_e32 v29, 0xffff0000, v30
	v_lshlrev_b32_e32 v30, 16, v31
	v_and_b32_e32 v31, 0xffff0000, v31
	v_pk_add_f32 v[26:27], v[24:25], v[26:27]
	v_pk_add_f32 v[24:25], v[42:43], v[52:53]
	v_pk_add_f32 v[30:31], v[46:47], v[30:31]
	v_pk_add_f32 v[28:29], v[44:45], v[28:29]

;     __device__ __forceinline__ void operator()(accv (&acc)[2][2][4][2], const pg8::Unit& u, int wr, int wc, int fr, int fq) const {
;     ...
;                 const int row = rowb + 128 * ai + 16 * m; float s = 0.f;
; #pragma unroll
;                 for (int bj = 0; bj < 2; ++bj) {
;                     const size_t off = (size_t)row * D + col0 + 128 * bj;
;                     F8 bs; if (basef) { bs.a = *(const f32x4*)(basef + off); bs.b = *(const f32x4*)(basef + off + 4); } else bs = split_load8(bhi, blo, off);
.LBB0_1360:
	s_or_b64 exec, exec, s[4:5]
	v_add_u32_e32 v24, 0xb0, v150
	v_ashrrev_i32_e32 v25, 31, v24
	v_lshlrev_b64 v[16:17], 10, v[24:25]
	v_lshl_add_u64 v[26:27], v[16:17], 0, v[148:149]
	s_and_b64 vcc, exec, s[10:11]
	v_lshl_add_u64 v[30:31], v[26:27], 2, s[20:21]
	s_cbranch_vccnz .LBB0_1363
	global_load_dwordx4 v[20:23], v[30:31], off offset:16 nt
	global_load_dwordx4 v[16:19], v[30:31], off nt
	s_mov_b64 s[4:5], 0
	s_branch .LBB0_1364

; __device__ __forceinline__ unsigned cvtpk(float lo, float hi) { f32x2_t v = {lo, hi}; bf16x2_t b = __builtin_convertvector(v, bf16x2_t); return __builtin_bit_cast(unsigned, b); }
; __device__ __forceinline__ void split_store8(bf16* hi, bf16* lo, size_t off, const F8& v) {
;     const v4u h = (v4u){cvtpk(v.a[0], v.a[1]), cvtpk(v.a[2], v.a[3]), cvtpk(v.b[0], v.b[1]), cvtpk(v.b[2], v.b[3])};
;     f32x4 ha, hb; unpack8(h, ha, hb);
;     const f32x4 ra = v.a - ha, rb = v.b - hb;
;     *(v4u*)(hi + off) = h;
;     *(v4u*)(lo + off) = (v4u){cvtpk(ra[0], ra[1]), cvtpk(ra[2], ra[3]), cvtpk(rb[0], rb[1]), cvtpk(rb[2], rb[3])};
; }
; __device__ __forceinline__ F8 split_load8(const bf16* hi, const bf16* lo, size_t off) {
;     const v4u h = *(const v4u*)(hi + off), l = *(const v4u*)(lo + off);
;     f32x4 ha, hb, la, lb; unpack8(h, ha, hb); unpack8(l, la, lb);
;     return F8{ha + la, hb + lb};
; }
;     __device__ __forceinline__ void operator()(accv (&acc)[2][2][4][2], const pg8::Unit& u, int wr, int wc, int fr, int fq) const {
;     ...
;                 const int row = rowb + 128 * ai + 16 * m; float s = 0.f;
; #pragma unroll
;                 for (int bj = 0; bj < 2; ++bj) {
;                     const size_t off = (size_t)row * D + col0 + 128 * bj;
;                     F8 bs; if (basef) { bs.a = *(const f32x4*)(basef + off); bs.b = *(const f32x4*)(basef + off + 4); } else bs = split_load8(bhi, blo, off);
;                     F8 v; v.a = bs.a + acc[ai][bj][m][0]; v.b = bs.b + acc[ai][bj][m][1];
;                     split_store8(ohi, olo, off, v);
;                     s += ((v.a[0] * v.a[0] + v.a[1] * v.a[1]) + (v.a[2] * v.a[2] + v.a[3] * v.a[3])) + ((v.b[0] * v.b[0] + v.b[1] * v.b[1]) + (v.b[2] * v.b[2] + v.b[3] * v.b[3]));
.LBB0_1364:
	v_lshlrev_b64 v[36:37], 1, v[26:27]
	s_andn2_b64 vcc, exec, s[4:5]
	v_lshl_add_u64 v[26:27], s[40:41], 0, v[36:37]
	v_lshl_add_u64 v[28:29], s[16:17], 0, v[36:37]
	s_cbranch_vccnz .LBB0_1366
	global_load_dwordx4 v[16:19], v[26:27], off nt
	global_load_dwordx4 v[20:23], v[28:29], off nt
	s_waitcnt vmcnt(1)
	v_lshlrev_b32_e32 v32, 16, v16
	v_and_b32_e32 v33, 0xffff0000, v16
	v_lshlrev_b32_e32 v16, 16, v17
	v_and_b32_e32 v17, 0xffff0000, v17
	v_lshlrev_b32_e32 v34, 16, v18
	v_and_b32_e32 v35, 0xffff0000, v18
	v_lshlrev_b32_e32 v38, 16, v19
	v_and_b32_e32 v39, 0xffff0000, v19
	s_waitcnt vmcnt(0)
	v_lshlrev_b32_e32 v40, 16, v20
	v_and_b32_e32 v41, 0xffff0000, v20
	v_lshlrev_b32_e32 v18, 16, v21
	v_and_b32_e32 v19, 0xffff0000, v21
	v_lshlrev_b32_e32 v20, 16, v22
	v_and_b32_e32 v21, 0xffff0000, v22
	v_lshlrev_b32_e32 v22, 16, v23
	v_and_b32_e32 v23, 0xffff0000, v23
	v_pk_add_f32 v[18:19], v[16:17], v[18:19]
	v_pk_add_f32 v[16:17], v[32:33], v[40:41]
	v_pk_add_f32 v[22:23], v[38:39], v[22:23]
	v_pk_add_f32 v[20:21], v[34:35], v[20:21]
.LBB0_1366:
	s_waitcnt vmcnt(0)
	v_pk_add_f32 v[32:33], v[14:15], v[18:19]
	v_pk_add_f32 v[34:35], v[12:13], v[16:17]
	v_pk_add_f32 v[22:23], v[10:11], v[22:23]
	v_pk_add_f32 v[20:21], v[8:9], v[20:21]
	v_cvt_pk_bf16_f32 v8, v34, v35
	v_cvt_pk_bf16_f32 v9, v32, v33
	v_cvt_pk_bf16_f32 v10, v20, v21
	v_cvt_pk_bf16_f32 v11, v22, v23
	v_lshlrev_b32_e32 v12, 16, v8
	v_and_b32_e32 v13, 0xffff0000, v8
	v_lshlrev_b32_e32 v14, 16, v9
	v_and_b32_e32 v15, 0xffff0000, v9
	v_lshlrev_b32_e32 v16, 16, v10
	v_and_b32_e32 v17, 0xffff0000, v10
	v_lshlrev_b32_e32 v18, 16, v11
	v_and_b32_e32 v19, 0xffff0000, v11
	v_sub_f32_e32 v15, v33, v15
	v_sub_f32_e32 v14, v32, v14
	v_sub_f32_e32 v13, v35, v13
	v_sub_f32_e32 v12, v34, v12
	v_sub_f32_e32 v38, v23, v19
	v_sub_f32_e32 v39, v22, v18
	v_sub_f32_e32 v17, v21, v17
	v_sub_f32_e32 v16, v20, v16
	v_lshl_add_u64 v[18:19], s[42:43], 0, v[36:37]
	global_store_dwordx4 v[18:19], v[8:11], off
	s_and_b64 vcc, exec, s[10:11]
	s_nop 0
	v_cvt_pk_bf16_f32 v8, v12, v13
	v_cvt_pk_bf16_f32 v9, v14, v15
	v_cvt_pk_bf16_f32 v10, v16, v17
	v_cvt_pk_bf16_f32 v11, v39, v38
	v_lshl_add_u64 v[16:17], s[44:45], 0, v[36:37]
	global_store_dwordx4 v[16:17], v[8:11], off
	s_cbranch_vccnz .LBB0_1374
	global_load_dwordx4 v[12:15], v[30:31], off offset:528 nt
	global_load_dwordx4 v[8:11], v[30:31], off offset:512 nt
	s_cbranch_execnz .LBB0_1369
.LBB0_1368:
	global_load_dwordx4 v[8:11], v[26:27], off offset:256 nt
	global_load_dwordx4 v[12:15], v[28:29], off offset:256 nt
	s_waitcnt vmcnt(1)
	v_lshlrev_b32_e32 v26, 16, v8
	v_and_b32_e32 v27, 0xffff0000, v8
	v_lshlrev_b32_e32 v8, 16, v9
	v_and_b32_e32 v9, 0xffff0000, v9
	v_lshlrev_b32_e32 v28, 16, v10
	v_and_b32_e32 v29, 0xffff0000, v10
	v_lshlrev_b32_e32 v30, 16, v11
	v_and_b32_e32 v31, 0xffff0000, v11
	s_waitcnt vmcnt(0)
	v_lshlrev_b32_e32 v36, 16, v12
	v_and_b32_e32 v37, 0xffff0000, v12
	v_lshlrev_b32_e32 v10, 16, v13
	v_and_b32_e32 v11, 0xffff0000, v13
	v_lshlrev_b32_e32 v12, 16, v14
	v_and_b32_e32 v13, 0xffff0000, v14
	v_lshlrev_b32_e32 v14, 16, v15
	v_and_b32_e32 v15, 0xffff0000, v15
	v_pk_add_f32 v[10:11], v[8:9], v[10:11]
	v_pk_add_f32 v[8:9], v[26:27], v[36:37]
	v_pk_add_f32 v[14:15], v[30:31], v[14:15]
	v_pk_add_f32 v[12:13], v[28:29], v[12:13]

; __device__ __forceinline__ float swap_sum(float v) { auto rr = __builtin_amdgcn_permlane32_swap(__float_as_uint(v), __float_as_uint(v), false, false); return __uint_as_float(rr[0]) + __uint_as_float(rr[1]); }
; __device__ __forceinline__ void load_rstd(const float* ss, int rowb, int fq, float (&rs)[2][4]) {
;     f32x4 p[2][4];
; #pragma unroll
;     for (int ai = 0; ai < 2; ++ai)
; #pragma unroll
;         for (int m = 0; m < 4; ++m) p[ai][m] = *(const f32x4*)(ss + (size_t)(rowb + 128 * ai + 16 * m) * 16 + 4 * fq);
; #pragma unroll
;     for (int ai = 0; ai < 2; ++ai)
; #pragma unroll
;         for (int m = 0; m < 4; ++m) {
;             float s = (p[ai][m][0] + p[ai][m][1]) + (p[ai][m][2] + p[ai][m][3]);
;             s += xshfl<16>(s); s = swap_sum(s);
;             rs[ai][m] = __builtin_amdgcn_rsqf(s * (1.0f / D) + EPS);
;         }
;     __device__ __forceinline__ void operator()(accv (&acc)[2][2][4][2], const pg8::Unit& u, int wr, int wc, int fr, int fq) const {
;     ...
;                 for (int bj = 0; bj < 2; ++bj) {
;                     const size_t off = (size_t)row * D + col0 + 128 * bj;
;                     const F8 x1 = split_load8(xhi, xlo, off); f32x4 pa, pb4; unpack8(*(const v4u*)(proj + off), pa, pb4);
;                     const accv a0 = acc[ai][bj][m][0] * rs[ai][m], a1 = acc[ai][bj][m][1] * rs[ai][m];
.LBB0_1468:
	s_lshl_b32 s0, s4, 8
	s_add_i32 s0, s0, s64
	v_mbcnt_lo_u32_b32 v220, -1, 0
	v_mbcnt_hi_u32_b32 v220, -1, v220
	s_mov_b64 s[4:5], -1
	v_ashrrev_i32_e32 v133, 4, v220
	v_and_or_b32 v132, v220, 15, s0
	s_lshl_b32 s0, s46, 8
	s_or_b32 s0, s0, s65
	v_lshlrev_b32_e32 v134, 2, v133
	v_lshl_add_u32 v146, v133, 3, s0
	v_ashrrev_i32_e32 v135, 31, v134
	v_ashrrev_i32_e32 v133, 31, v132
	v_lshl_add_u64 v[134:135], v[134:135], 2, s[12:13]
	v_lshlrev_b64 v[174:175], 6, v[132:133]
	v_lshl_add_u64 v[144:145], v[134:135], 0, v[174:175]
	global_load_dwordx4 v[176:179], v[144:145], off nt
	v_or_b32_e32 v172, 16, v132
	v_ashrrev_i32_e32 v173, 31, v172
	v_lshlrev_b64 v[170:171], 6, v[172:173]
	v_lshl_add_u64 v[144:145], v[134:135], 0, v[170:171]
	global_load_dwordx4 v[180:183], v[144:145], off nt
	v_or_b32_e32 v168, 32, v132
	v_ashrrev_i32_e32 v169, 31, v168
	v_lshlrev_b64 v[166:167], 6, v[168:169]
	v_lshl_add_u64 v[144:145], v[134:135], 0, v[166:167]
	global_load_dwordx4 v[184:187], v[144:145], off nt
	v_or_b32_e32 v164, 48, v132
	v_ashrrev_i32_e32 v165, 31, v164
	v_lshlrev_b64 v[162:163], 6, v[164:165]
	v_lshl_add_u64 v[144:145], v[134:135], 0, v[162:163]
	global_load_dwordx4 v[188:191], v[144:145], off nt
	v_add_u32_e32 v160, 0x80, v132
	v_ashrrev_i32_e32 v161, 31, v160
	v_lshlrev_b64 v[158:159], 6, v[160:161]
	v_lshl_add_u64 v[144:145], v[134:135], 0, v[158:159]
	global_load_dwordx4 v[198:201], v[144:145], off nt
	v_add_u32_e32 v156, 0x90, v132
	v_ashrrev_i32_e32 v157, 31, v156
	v_lshlrev_b64 v[154:155], 6, v[156:157]
	v_lshl_add_u64 v[144:145], v[134:135], 0, v[154:155]
	global_load_dwordx4 v[202:205], v[144:145], off nt
	v_add_u32_e32 v152, 0xa0, v132
	v_ashrrev_i32_e32 v153, 31, v152
	v_lshlrev_b64 v[150:151], 6, v[152:153]
	v_lshl_add_u64 v[144:145], v[134:135], 0, v[150:151]
	global_load_dwordx4 v[208:211], v[144:145], off nt
	v_add_u32_e32 v148, 0xb0, v132
	v_ashrrev_i32_e32 v149, 31, v148
	v_lshlrev_b64 v[144:145], 6, v[148:149]
	v_lshl_add_u64 v[134:135], v[134:135], 0, v[144:145]
	global_load_dwordx4 v[224:227], v[134:135], off nt
	v_ashrrev_i32_e32 v147, 31, v146
	v_lshlrev_b64 v[132:133], 10, v[132:133]
	s_andn2_b64 vcc, exec, s[48:49]
	s_waitcnt vmcnt(0)
	v_add_f32_e32 v134, v176, v177
	v_add_f32_e32 v135, v178, v179
	v_add_f32_e32 v134, v134, v135
	ds_swizzle_b32 v135, v134 offset:swizzle(SWAP,16)
	s_waitcnt lgkmcnt(0)
	v_add_f32_e32 v134, v134, v135
	v_mov_b32_e32 v135, v134
	s_nop 1
	v_permlane32_swap_b32_e32 v134, v135
	v_add_f32_e32 v134, v134, v135
	v_fmamk_f32 v134, v134, 0x3a800000, v237
	v_rsq_f32_e32 v223, v134
	v_add_f32_e32 v134, v180, v181
	v_add_f32_e32 v135, v182, v183
	v_add_f32_e32 v134, v134, v135
	ds_swizzle_b32 v135, v134 offset:swizzle(SWAP,16)
	v_lshl_add_u64 v[182:183], v[132:133], 0, v[146:147]
	v_lshlrev_b64 v[180:181], 1, v[182:183]
	v_lshl_add_u64 v[176:177], s[2:3], 0, v[180:181]
	v_lshl_add_u64 v[178:179], s[10:11], 0, v[180:181]
	s_waitcnt lgkmcnt(0)
	v_add_f32_e32 v221, v134, v135
	v_add_f32_e32 v134, v184, v185
	v_add_f32_e32 v135, v186, v187
	v_add_f32_e32 v134, v134, v135
	ds_swizzle_b32 v135, v134 offset:swizzle(SWAP,16)
	v_mul_f32_e32 v124, v124, v223
	v_mul_f32_e32 v128, v128, v223
	v_mul_f32_e32 v124, 0xbfb8aa3b, v124
	v_mul_f32_e32 v126, v126, v223
	s_waitcnt lgkmcnt(0)
	v_add_f32_e32 v218, v134, v135
	v_add_f32_e32 v134, v188, v189
	v_add_f32_e32 v135, v190, v191
	v_add_f32_e32 v134, v134, v135
	ds_swizzle_b32 v135, v134 offset:swizzle(SWAP,16)
	v_mul_f32_e32 v128, 0xbfb8aa3b, v128
	v_exp_f32_e32 v124, v124
	v_mul_f32_e32 v126, 0xbfb8aa3b, v126
	v_exp_f32_e32 v128, v128
	s_waitcnt lgkmcnt(0)
	v_add_f32_e32 v216, v134, v135
	v_add_f32_e32 v134, v198, v199
	v_add_f32_e32 v135, v200, v201
	v_add_f32_e32 v134, v134, v135
	ds_swizzle_b32 v135, v134 offset:swizzle(SWAP,16)
	v_exp_f32_e32 v126, v126
	v_add_f32_e32 v124, 1.0, v124
	v_add_f32_e32 v128, 1.0, v128
	v_mul_f32_e32 v125, v125, v223
	s_waitcnt lgkmcnt(0)
; __device__ __forceinline__ float sigmoidf_(float x) { return __builtin_amdgcn_rcpf(1.f + fexp2(-1.4426950408889634f * x)); }
;     __device__ __forceinline__ void operator()(accv (&acc)[2][2][4][2], const pg8::Unit& u, int wr, int wc, int fr, int fq) const {
;     ...
;                 for (int bj = 0; bj < 2; ++bj) {
;                     const size_t off = (size_t)row * D + col0 + 128 * bj;
;                     const F8 x1 = split_load8(xhi, xlo, off); f32x4 pa, pb4; unpack8(*(const v4u*)(proj + off), pa, pb4);
;                     const accv a0 = acc[ai][bj][m][0] * rs[ai][m], a1 = acc[ai][bj][m][1] * rs[ai][m];
;                     F8 v;
; #pragma unroll
;                     for (int i = 0; i < 4; ++i) { v.a[i] = x1.a[i] + sigmoidf_(a0[i]) * pa[i]; v.b[i] = x1.b[i] + sigmoidf_(a1[i]) * pb4[i]; }
;                     if (outf) { *(f32x4*)(outf + off) = v.a; *(f32x4*)(outf + off + 4) = v.b; }
	v_add_f32_e32 v214, v134, v135
	v_add_f32_e32 v134, v202, v203
	v_add_f32_e32 v135, v204, v205
	v_add_f32_e32 v134, v134, v135
	ds_swizzle_b32 v135, v134 offset:swizzle(SWAP,16)
	global_load_dwordx4 v[184:187], v[178:179], off nt
	v_lshl_add_u64 v[204:205], s[18:19], 0, v[180:181]
	v_add_f32_e32 v126, 1.0, v126
	v_mul_f32_e32 v125, 0xbfb8aa3b, v125
	s_waitcnt lgkmcnt(0)
	v_add_f32_e32 v212, v134, v135
	v_add_f32_e32 v134, v208, v209
	v_add_f32_e32 v135, v210, v211
	v_add_f32_e32 v134, v134, v135
	ds_swizzle_b32 v135, v134 offset:swizzle(SWAP,16)
	v_mul_f32_e32 v127, v127, v223
	v_exp_f32_e32 v125, v125
	v_mul_f32_e32 v127, 0xbfb8aa3b, v127
	v_exp_f32_e32 v127, v127
	s_waitcnt lgkmcnt(0)
	v_add_f32_e32 v210, v134, v135
	v_add_f32_e32 v134, v224, v225
	v_add_f32_e32 v135, v226, v227
	v_add_f32_e32 v134, v134, v135
	ds_swizzle_b32 v135, v134 offset:swizzle(SWAP,16)
	v_add_f32_e32 v125, 1.0, v125
	v_rcp_f32_e32 v125, v125
	v_add_f32_e32 v127, 1.0, v127
	v_rcp_f32_e32 v127, v127
	s_waitcnt lgkmcnt(0)
	v_add_f32_e32 v208, v134, v135
	global_load_dwordx4 v[132:135], v[176:177], off nt
	v_mov_b32_e32 v222, v221
	v_mov_b32_e32 v219, v218
	v_mov_b32_e32 v217, v216
	v_mov_b32_e32 v215, v214
	v_mov_b32_e32 v213, v212
	v_mov_b32_e32 v211, v210
	v_mov_b32_e32 v209, v208
	v_permlane32_swap_b32_e32 v221, v222
	v_permlane32_swap_b32_e32 v218, v219
	v_permlane32_swap_b32_e32 v216, v217
	v_permlane32_swap_b32_e32 v214, v215
	v_permlane32_swap_b32_e32 v212, v213
	v_permlane32_swap_b32_e32 v210, v211
	v_permlane32_swap_b32_e32 v208, v209
	s_waitcnt vmcnt(1)
	v_lshlrev_b32_e32 v192, 16, v184
	v_and_b32_e32 v193, 0xffff0000, v184
	v_lshlrev_b32_e32 v184, 16, v185
	v_and_b32_e32 v185, 0xffff0000, v185
	v_lshlrev_b32_e32 v202, 16, v186
	v_and_b32_e32 v203, 0xffff0000, v186
	v_lshlrev_b32_e32 v186, 16, v187
	v_and_b32_e32 v187, 0xffff0000, v187
	s_waitcnt vmcnt(0)
	v_lshlrev_b32_e32 v188, 16, v132
	v_and_b32_e32 v189, 0xffff0000, v132
	v_lshlrev_b32_e32 v132, 16, v133
	v_and_b32_e32 v133, 0xffff0000, v133
	v_lshlrev_b32_e32 v190, 16, v134
	v_and_b32_e32 v191, 0xffff0000, v134
	v_lshlrev_b32_e32 v134, 16, v135
	v_and_b32_e32 v135, 0xffff0000, v135
	v_pk_add_f32 v[184:185], v[132:133], v[184:185]
	v_pk_add_f32 v[198:199], v[134:135], v[186:187]
	global_load_dwordx4 v[132:135], v[204:205], off nt
	v_rcp_f32_e32 v187, v124
	v_mul_f32_e32 v124, v129, v223
	v_rcp_f32_e32 v186, v128
	v_mul_f32_e32 v124, 0xbfb8aa3b, v124
	v_mul_f32_e32 v128, v130, v223
	v_rcp_f32_e32 v129, v126
	v_mul_f32_e32 v126, v131, v223
	v_exp_f32_e32 v124, v124
	v_mul_f32_e32 v128, 0xbfb8aa3b, v128
	v_mul_f32_e32 v126, 0xbfb8aa3b, v126
	v_exp_f32_e32 v128, v128
	v_exp_f32_e32 v126, v126
	v_add_f32_e32 v124, 1.0, v124
	v_rcp_f32_e32 v124, v124
	v_add_f32_e32 v128, 1.0, v128
	v_add_f32_e32 v126, 1.0, v126
	v_rcp_f32_e32 v128, v128
	v_rcp_f32_e32 v126, v126
	v_pk_add_f32 v[200:201], v[188:189], v[192:193]
	v_pk_add_f32 v[202:203], v[190:191], v[202:203]
	s_waitcnt vmcnt(0)
	v_lshlrev_b32_e32 v131, 16, v134
	v_lshlrev_b32_e32 v130, 16, v132
	v_and_b32_e32 v189, 0xffff0000, v134
	v_and_b32_e32 v188, 0xffff0000, v132
	v_lshlrev_b32_e32 v190, 16, v133
	v_and_b32_e32 v192, 0xffff0000, v133
	v_mov_b32_e32 v132, v200
	v_mov_b32_e32 v133, v202
	v_mov_b32_e32 v202, v201
	v_lshlrev_b32_e32 v191, 16, v135
	v_and_b32_e32 v193, 0xffff0000, v135
	v_pk_fma_f32 v[134:135], v[186:187], v[130:131], v[132:133]
	v_pk_fma_f32 v[200:201], v[124:125], v[188:189], v[202:203]
	v_mov_b32_e32 v124, v184
	v_mov_b32_e32 v125, v198
	v_mov_b32_e32 v198, v185
	v_cndmask_b32_e64 v132, 0, 1, s[48:49]
	v_pk_fma_f32 v[202:203], v[128:129], v[190:191], v[124:125]
	v_pk_fma_f32 v[184:185], v[126:127], v[192:193], v[198:199]
	v_cmp_ne_u32_e64 s[42:43], 1, v132
	v_lshl_add_u64 v[132:133], v[182:183], 2, s[20:21]
	s_cbranch_vccnz .LBB0_1470
	v_mov_b32_e32 v124, v134
	v_mov_b32_e32 v125, v200
	v_mov_b32_e32 v126, v202
	v_mov_b32_e32 v127, v184
	s_mov_b64 s[4:5], 0
	v_mov_b32_e32 v128, v135
	v_mov_b32_e32 v129, v201
	v_mov_b32_e32 v130, v203
	v_mov_b32_e32 v131, v185
	global_store_dwordx4 v[132:133], v[124:127], off
	global_store_dwordx4 v[132:133], v[128:131], off offset:16

; __device__ __forceinline__ float sigmoidf_(float x) { return __builtin_amdgcn_rcpf(1.f + fexp2(-1.4426950408889634f * x)); }
;     __device__ __forceinline__ void operator()(accv (&acc)[2][2][4][2], const pg8::Unit& u, int wr, int wc, int fr, int fq) const {
;     ...
;                 for (int bj = 0; bj < 2; ++bj) {
;                     const size_t off = (size_t)row * D + col0 + 128 * bj;
;                     const F8 x1 = split_load8(xhi, xlo, off); f32x4 pa, pb4; unpack8(*(const v4u*)(proj + off), pa, pb4);
;                     const accv a0 = acc[ai][bj][m][0] * rs[ai][m], a1 = acc[ai][bj][m][1] * rs[ai][m];
;                     F8 v;
; #pragma unroll
;                     for (int i = 0; i < 4; ++i) { v.a[i] = x1.a[i] + sigmoidf_(a0[i]) * pa[i]; v.b[i] = x1.b[i] + sigmoidf_(a1[i]) * pb4[i]; }
;                     if (outf) { *(f32x4*)(outf + off) = v.a; *(f32x4*)(outf + off + 4) = v.b; }
.LBB0_1472:
	global_load_dwordx4 v[124:127], v[176:177], off offset:256 nt
	s_nop 0
	global_load_dwordx4 v[176:179], v[178:179], off offset:256 nt
	v_mul_f32_e32 v116, v116, v223
	v_mul_f32_e32 v120, v120, v223
	v_mul_f32_e32 v116, 0xbfb8aa3b, v116
	v_mul_f32_e32 v118, v118, v223
	v_mul_f32_e32 v120, 0xbfb8aa3b, v120
	v_exp_f32_e32 v116, v116
	v_mul_f32_e32 v118, 0xbfb8aa3b, v118
	v_exp_f32_e32 v120, v120
	v_exp_f32_e32 v118, v118
	v_add_f32_e32 v116, 1.0, v116
	v_mul_f32_e32 v117, v117, v223
	v_add_f32_e32 v120, 1.0, v120
	v_add_f32_e32 v118, 1.0, v118
	v_mul_f32_e32 v117, 0xbfb8aa3b, v117
	v_mul_f32_e32 v119, v119, v223
	v_exp_f32_e32 v117, v117
	v_mul_f32_e32 v119, 0xbfb8aa3b, v119
	v_exp_f32_e32 v119, v119
	s_mov_b64 s[4:5], -1
	v_add_f32_e32 v117, 1.0, v117
	v_rcp_f32_e32 v117, v117
	v_add_f32_e32 v119, 1.0, v119
	v_rcp_f32_e32 v119, v119
	s_and_b64 vcc, exec, s[42:43]
	s_waitcnt vmcnt(1)
	v_lshlrev_b32_e32 v134, 16, v124
	v_and_b32_e32 v135, 0xffff0000, v124
	v_lshlrev_b32_e32 v124, 16, v125
	v_and_b32_e32 v125, 0xffff0000, v125
	v_lshlrev_b32_e32 v180, 16, v126
	v_and_b32_e32 v181, 0xffff0000, v126
	v_lshlrev_b32_e32 v126, 16, v127
	v_and_b32_e32 v127, 0xffff0000, v127
	s_waitcnt vmcnt(0)
	v_lshlrev_b32_e32 v182, 16, v176
	v_and_b32_e32 v183, 0xffff0000, v176
	v_lshlrev_b32_e32 v176, 16, v177
	v_and_b32_e32 v177, 0xffff0000, v177
	v_lshlrev_b32_e32 v186, 16, v179
	v_and_b32_e32 v187, 0xffff0000, v179
	v_lshlrev_b32_e32 v184, 16, v178
	v_and_b32_e32 v185, 0xffff0000, v178
	v_pk_add_f32 v[176:177], v[124:125], v[176:177]
	v_pk_add_f32 v[178:179], v[134:135], v[182:183]
	v_pk_add_f32 v[134:135], v[126:127], v[186:187]
	global_load_dwordx4 v[124:127], v[204:205], off offset:256 nt
	v_rcp_f32_e32 v183, v116
	v_mul_f32_e32 v116, v121, v223
	v_rcp_f32_e32 v182, v120
	v_mul_f32_e32 v116, 0xbfb8aa3b, v116
	v_mul_f32_e32 v120, v122, v223
	v_rcp_f32_e32 v121, v118
	v_mul_f32_e32 v118, v123, v223
	v_exp_f32_e32 v116, v116
	v_mul_f32_e32 v120, 0xbfb8aa3b, v120
	v_mul_f32_e32 v118, 0xbfb8aa3b, v118
	v_exp_f32_e32 v120, v120
	v_exp_f32_e32 v118, v118
	v_add_f32_e32 v116, 1.0, v116
	v_rcp_f32_e32 v116, v116
	v_add_f32_e32 v120, 1.0, v120
	v_add_f32_e32 v118, 1.0, v118
	v_rcp_f32_e32 v120, v120
	v_rcp_f32_e32 v118, v118
	v_pk_add_f32 v[180:181], v[180:181], v[184:185]
	s_waitcnt vmcnt(0)
	v_and_b32_e32 v185, 0xffff0000, v126
	v_and_b32_e32 v184, 0xffff0000, v124
	v_lshlrev_b32_e32 v186, 16, v125
	v_and_b32_e32 v188, 0xffff0000, v125
	v_mov_b32_e32 v125, v180
	v_mov_b32_e32 v180, v179
	v_lshlrev_b32_e32 v123, 16, v126
	v_lshlrev_b32_e32 v122, 16, v124
	v_lshlrev_b32_e32 v187, 16, v127
	v_and_b32_e32 v189, 0xffff0000, v127
	v_mov_b32_e32 v124, v178
	v_pk_fma_f32 v[126:127], v[116:117], v[184:185], v[180:181]
	v_mov_b32_e32 v116, v176
	v_mov_b32_e32 v117, v134
	v_mov_b32_e32 v134, v177
	v_pk_fma_f32 v[124:125], v[182:183], v[122:123], v[124:125]
	v_pk_fma_f32 v[178:179], v[120:121], v[186:187], v[116:117]
	v_pk_fma_f32 v[134:135], v[118:119], v[188:189], v[134:135]
	s_cbranch_vccnz .LBB0_1474
	v_mov_b32_e32 v116, v124
	v_mov_b32_e32 v117, v126
	v_mov_b32_e32 v118, v178
	v_mov_b32_e32 v119, v134
	s_mov_b64 s[4:5], 0
	v_mov_b32_e32 v120, v125
	v_mov_b32_e32 v121, v127
	v_mov_b32_e32 v122, v179
	v_mov_b32_e32 v123, v135
	global_store_dwordx4 v[132:133], v[116:119], off offset:512
	global_store_dwordx4 v[132:133], v[120:123], off offset:528

; __device__ __forceinline__ float sigmoidf_(float x) { return __builtin_amdgcn_rcpf(1.f + fexp2(-1.4426950408889634f * x)); }
;     __device__ __forceinline__ void operator()(accv (&acc)[2][2][4][2], const pg8::Unit& u, int wr, int wc, int fr, int fq) const {
;     ...
;                 for (int bj = 0; bj < 2; ++bj) {
;                     const size_t off = (size_t)row * D + col0 + 128 * bj;
;                     const F8 x1 = split_load8(xhi, xlo, off); f32x4 pa, pb4; unpack8(*(const v4u*)(proj + off), pa, pb4);
;                     const accv a0 = acc[ai][bj][m][0] * rs[ai][m], a1 = acc[ai][bj][m][1] * rs[ai][m];
;                     F8 v;
; #pragma unroll
;                     for (int i = 0; i < 4; ++i) { v.a[i] = x1.a[i] + sigmoidf_(a0[i]) * pa[i]; v.b[i] = x1.b[i] + sigmoidf_(a1[i]) * pb4[i]; }
;                     if (outf) { *(f32x4*)(outf + off) = v.a; *(f32x4*)(outf + off + 4) = v.b; }
.LBB0_1480:
	v_add_f32_e32 v116, v221, v222
	v_fmamk_f32 v116, v116, 0x3a800000, v237
	v_rsq_f32_e32 v176, v116
	v_lshlrev_b64 v[116:117], 10, v[172:173]
	v_lshl_add_u64 v[128:129], v[116:117], 0, v[146:147]
	v_lshlrev_b64 v[126:127], 1, v[128:129]
	v_lshl_add_u64 v[120:121], s[2:3], 0, v[126:127]
	v_lshl_add_u64 v[122:123], s[10:11], 0, v[126:127]
	global_load_dwordx4 v[116:119], v[120:121], off nt
	global_load_dwordx4 v[130:133], v[122:123], off nt
	v_mul_f32_e32 v104, v104, v176
	v_mul_f32_e32 v104, 0xbfb8aa3b, v104
	v_exp_f32_e32 v104, v104
	v_mul_f32_e32 v108, v108, v176
	v_mul_f32_e32 v108, 0xbfb8aa3b, v108
	v_exp_f32_e32 v108, v108
	v_add_f32_e32 v104, 1.0, v104
	s_mov_b64 s[4:5], -1
	s_and_b64 vcc, exec, s[42:43]
	v_add_f32_e32 v108, 1.0, v108
	s_waitcnt vmcnt(1)
	v_lshlrev_b32_e32 v124, 16, v116
	v_and_b32_e32 v125, 0xffff0000, v116
	s_waitcnt vmcnt(0)
	v_lshlrev_b32_e32 v134, 16, v130
	v_and_b32_e32 v135, 0xffff0000, v130
	v_lshlrev_b32_e32 v116, 16, v117
	v_and_b32_e32 v117, 0xffff0000, v117
	v_lshlrev_b32_e32 v172, 16, v118
	v_and_b32_e32 v173, 0xffff0000, v118
	v_lshlrev_b32_e32 v118, 16, v119
	v_and_b32_e32 v119, 0xffff0000, v119
	v_lshlrev_b32_e32 v130, 16, v131
	v_and_b32_e32 v131, 0xffff0000, v131
	v_lshlrev_b32_e32 v174, 16, v132
	v_and_b32_e32 v175, 0xffff0000, v132
	v_lshlrev_b32_e32 v132, 16, v133
	v_and_b32_e32 v133, 0xffff0000, v133
	v_pk_add_f32 v[134:135], v[124:125], v[134:135]
	v_lshl_add_u64 v[124:125], s[18:19], 0, v[126:127]
	v_pk_add_f32 v[130:131], v[116:117], v[130:131]
	v_pk_add_f32 v[132:133], v[118:119], v[132:133]
	global_load_dwordx4 v[116:119], v[124:125], off nt
	v_pk_add_f32 v[172:173], v[172:173], v[174:175]
	v_rcp_f32_e32 v174, v104
	v_mul_f32_e32 v104, v109, v176
	v_mul_f32_e32 v104, 0xbfb8aa3b, v104
	v_exp_f32_e32 v104, v104
	v_rcp_f32_e32 v175, v108
	v_add_f32_e32 v104, 1.0, v104
	v_rcp_f32_e32 v109, v104
	v_mul_f32_e32 v104, v105, v176
	v_mul_f32_e32 v104, 0xbfb8aa3b, v104
	v_exp_f32_e32 v104, v104
	s_waitcnt vmcnt(0)
	v_and_b32_e32 v179, 0xffff0000, v116
	v_add_f32_e32 v104, 1.0, v104
	v_rcp_f32_e32 v108, v104
	v_mul_f32_e32 v104, v110, v176
	v_mul_f32_e32 v104, 0xbfb8aa3b, v104
	v_exp_f32_e32 v104, v104
	v_and_b32_e32 v178, 0xffff0000, v118
	v_lshlrev_b32_e32 v180, 16, v119
	v_lshlrev_b32_e32 v181, 16, v117
	v_add_f32_e32 v104, 1.0, v104
	v_rcp_f32_e32 v105, v104
	v_mul_f32_e32 v104, v106, v176
	v_mul_f32_e32 v106, v111, v176
	v_mul_f32_e32 v106, 0xbfb8aa3b, v106
	v_exp_f32_e32 v106, v106
	v_mul_f32_e32 v104, 0xbfb8aa3b, v104
	v_exp_f32_e32 v104, v104
	v_and_b32_e32 v117, 0xffff0000, v117
	v_add_f32_e32 v106, 1.0, v106
	v_rcp_f32_e32 v111, v106
	v_mul_f32_e32 v106, v107, v176
	v_mul_f32_e32 v106, 0xbfb8aa3b, v106
	v_exp_f32_e32 v106, v106
	v_add_f32_e32 v104, 1.0, v104
	v_rcp_f32_e32 v104, v104
	v_lshlrev_b32_e32 v107, 16, v116
	v_add_f32_e32 v106, 1.0, v106
	v_rcp_f32_e32 v110, v106
	v_lshlrev_b32_e32 v106, 16, v118
	v_and_b32_e32 v116, 0xffff0000, v119
	v_mov_b32_e32 v118, v172
	v_mov_b32_e32 v119, v134
	v_pk_fma_f32 v[118:119], v[174:175], v[106:107], v[118:119]
	v_mov_b32_e32 v134, v173
	v_mov_b32_e32 v106, v132
	v_mov_b32_e32 v107, v130
	v_mov_b32_e32 v130, v133
	v_pk_fma_f32 v[134:135], v[108:109], v[178:179], v[134:135]
	v_pk_fma_f32 v[172:173], v[104:105], v[180:181], v[106:107]
	v_pk_fma_f32 v[130:131], v[110:111], v[116:117], v[130:131]
	v_lshl_add_u64 v[116:117], v[128:129], 2, s[20:21]
	s_cbranch_vccnz .LBB0_1482
	v_mov_b32_e32 v104, v119
	v_mov_b32_e32 v105, v135
	v_mov_b32_e32 v106, v173
	v_mov_b32_e32 v107, v131
	s_mov_b64 s[4:5], 0
	v_mov_b32_e32 v108, v118
	v_mov_b32_e32 v109, v134
	v_mov_b32_e32 v110, v172
	v_mov_b32_e32 v111, v130
	global_store_dwordx4 v[116:117], v[104:107], off
	global_store_dwordx4 v[116:117], v[108:111], off offset:16

; __device__ __forceinline__ float sigmoidf_(float x) { return __builtin_amdgcn_rcpf(1.f + fexp2(-1.4426950408889634f * x)); }
;     __device__ __forceinline__ void operator()(accv (&acc)[2][2][4][2], const pg8::Unit& u, int wr, int wc, int fr, int fq) const {
;     ...
;                 for (int bj = 0; bj < 2; ++bj) {
;                     const size_t off = (size_t)row * D + col0 + 128 * bj;
;                     const F8 x1 = split_load8(xhi, xlo, off); f32x4 pa, pb4; unpack8(*(const v4u*)(proj + off), pa, pb4);
;                     const accv a0 = acc[ai][bj][m][0] * rs[ai][m], a1 = acc[ai][bj][m][1] * rs[ai][m];
;                     F8 v;
; #pragma unroll
;                     for (int i = 0; i < 4; ++i) { v.a[i] = x1.a[i] + sigmoidf_(a0[i]) * pa[i]; v.b[i] = x1.b[i] + sigmoidf_(a1[i]) * pb4[i]; }
;                     if (outf) { *(f32x4*)(outf + off) = v.a; *(f32x4*)(outf + off + 4) = v.b; }
.LBB0_1484:
	global_load_dwordx4 v[104:107], v[120:121], off offset:256 nt
	s_nop 0
	global_load_dwordx4 v[118:121], v[122:123], off offset:256 nt
	v_mul_f32_e32 v96, v96, v176
	v_mul_f32_e32 v100, v100, v176
	v_mul_f32_e32 v96, 0xbfb8aa3b, v96
	v_mul_f32_e32 v98, v98, v176
	v_mul_f32_e32 v100, 0xbfb8aa3b, v100
	v_exp_f32_e32 v96, v96
	v_mul_f32_e32 v98, 0xbfb8aa3b, v98
	v_exp_f32_e32 v100, v100
	v_exp_f32_e32 v98, v98
	v_add_f32_e32 v96, 1.0, v96
	v_mul_f32_e32 v97, v97, v176
	v_add_f32_e32 v100, 1.0, v100
	v_add_f32_e32 v98, 1.0, v98
	v_mul_f32_e32 v97, 0xbfb8aa3b, v97
	v_mul_f32_e32 v99, v99, v176
	v_exp_f32_e32 v97, v97
	v_mul_f32_e32 v99, 0xbfb8aa3b, v99
	v_exp_f32_e32 v99, v99
	s_mov_b64 s[4:5], -1
	v_add_f32_e32 v97, 1.0, v97
	v_rcp_f32_e32 v97, v97
	v_add_f32_e32 v99, 1.0, v99
	v_rcp_f32_e32 v99, v99
	s_and_b64 vcc, exec, s[42:43]
	s_waitcnt vmcnt(1)
	v_lshlrev_b32_e32 v122, 16, v104
	v_and_b32_e32 v123, 0xffff0000, v104
	v_lshlrev_b32_e32 v104, 16, v105
	v_and_b32_e32 v105, 0xffff0000, v105
	v_lshlrev_b32_e32 v126, 16, v106
	v_and_b32_e32 v127, 0xffff0000, v106
	v_lshlrev_b32_e32 v106, 16, v107
	v_and_b32_e32 v107, 0xffff0000, v107
	s_waitcnt vmcnt(0)
	v_lshlrev_b32_e32 v130, 16, v118
	v_and_b32_e32 v131, 0xffff0000, v118
	v_lshlrev_b32_e32 v118, 16, v119
	v_and_b32_e32 v119, 0xffff0000, v119
	v_lshlrev_b32_e32 v134, 16, v121
	v_and_b32_e32 v135, 0xffff0000, v121
	v_lshlrev_b32_e32 v132, 16, v120
	v_and_b32_e32 v133, 0xffff0000, v120
	v_pk_add_f32 v[120:121], v[104:105], v[118:119]
	v_pk_add_f32 v[118:119], v[106:107], v[134:135]
	global_load_dwordx4 v[104:107], v[124:125], off offset:256 nt
	v_rcp_f32_e32 v125, v96
	v_mul_f32_e32 v96, v101, v176
	v_rcp_f32_e32 v124, v100
	v_mul_f32_e32 v96, 0xbfb8aa3b, v96
	v_mul_f32_e32 v100, v102, v176
	v_rcp_f32_e32 v101, v98
	v_mul_f32_e32 v98, v103, v176
	v_exp_f32_e32 v96, v96
	v_mul_f32_e32 v100, 0xbfb8aa3b, v100
	v_mul_f32_e32 v98, 0xbfb8aa3b, v98
	v_exp_f32_e32 v100, v100
	v_exp_f32_e32 v98, v98
	v_add_f32_e32 v96, 1.0, v96
	v_rcp_f32_e32 v96, v96
	v_add_f32_e32 v100, 1.0, v100
	v_add_f32_e32 v98, 1.0, v98
	v_rcp_f32_e32 v100, v100
	v_rcp_f32_e32 v98, v98
	v_pk_add_f32 v[122:123], v[122:123], v[130:131]
	v_pk_add_f32 v[126:127], v[126:127], v[132:133]
	s_waitcnt vmcnt(0)
	v_and_b32_e32 v131, 0xffff0000, v106
	v_and_b32_e32 v130, 0xffff0000, v104
	v_lshlrev_b32_e32 v132, 16, v105
	v_and_b32_e32 v134, 0xffff0000, v105
	v_mov_b32_e32 v105, v126
	v_mov_b32_e32 v126, v123
	v_lshlrev_b32_e32 v103, 16, v106
	v_lshlrev_b32_e32 v102, 16, v104
	v_lshlrev_b32_e32 v133, 16, v107
	v_and_b32_e32 v135, 0xffff0000, v107
	v_mov_b32_e32 v104, v122
	v_pk_fma_f32 v[106:107], v[96:97], v[130:131], v[126:127]
	v_mov_b32_e32 v96, v120
	v_mov_b32_e32 v97, v118
	v_mov_b32_e32 v118, v121
	v_pk_fma_f32 v[104:105], v[124:125], v[102:103], v[104:105]
	v_pk_fma_f32 v[122:123], v[100:101], v[132:133], v[96:97]
	v_pk_fma_f32 v[118:119], v[98:99], v[134:135], v[118:119]
	s_cbranch_vccnz .LBB0_1487
	v_mov_b32_e32 v96, v104
	v_mov_b32_e32 v97, v106
	v_mov_b32_e32 v98, v122
	v_mov_b32_e32 v99, v118
	v_mov_b32_e32 v100, v105
	v_mov_b32_e32 v101, v107
	v_mov_b32_e32 v102, v123
	v_mov_b32_e32 v103, v119
	global_store_dwordx4 v[116:117], v[96:99], off offset:512
	global_store_dwordx4 v[116:117], v[100:103], off offset:528
	s_cbranch_execz .LBB0_1488

; __device__ __forceinline__ float sigmoidf_(float x) { return __builtin_amdgcn_rcpf(1.f + fexp2(-1.4426950408889634f * x)); }
;     __device__ __forceinline__ void operator()(accv (&acc)[2][2][4][2], const pg8::Unit& u, int wr, int wc, int fr, int fq) const {
;     ...
;                 for (int bj = 0; bj < 2; ++bj) {
;                     const size_t off = (size_t)row * D + col0 + 128 * bj;
;                     const F8 x1 = split_load8(xhi, xlo, off); f32x4 pa, pb4; unpack8(*(const v4u*)(proj + off), pa, pb4);
;                     const accv a0 = acc[ai][bj][m][0] * rs[ai][m], a1 = acc[ai][bj][m][1] * rs[ai][m];
;                     F8 v;
; #pragma unroll
;                     for (int i = 0; i < 4; ++i) { v.a[i] = x1.a[i] + sigmoidf_(a0[i]) * pa[i]; v.b[i] = x1.b[i] + sigmoidf_(a1[i]) * pb4[i]; }
;                     if (outf) { *(f32x4*)(outf + off) = v.a; *(f32x4*)(outf + off + 4) = v.b; }
.LBB0_1492:
	v_add_f32_e32 v96, v218, v219
	v_fmamk_f32 v96, v96, 0x3a800000, v237
	v_rsq_f32_e32 v124, v96
	v_lshlrev_b64 v[96:97], 10, v[168:169]
	v_lshl_add_u64 v[108:109], v[96:97], 0, v[146:147]
	v_lshlrev_b64 v[106:107], 1, v[108:109]
	v_lshl_add_u64 v[100:101], s[2:3], 0, v[106:107]
	v_lshl_add_u64 v[102:103], s[10:11], 0, v[106:107]
	global_load_dwordx4 v[96:99], v[100:101], off nt
	global_load_dwordx4 v[116:119], v[102:103], off nt
	v_mul_f32_e32 v88, v88, v124
	v_mul_f32_e32 v88, 0xbfb8aa3b, v88
	v_exp_f32_e32 v88, v88
	v_mul_f32_e32 v92, v92, v124
	v_mul_f32_e32 v92, 0xbfb8aa3b, v92
	v_exp_f32_e32 v92, v92
	v_add_f32_e32 v88, 1.0, v88
	s_mov_b64 s[4:5], -1
	s_and_b64 vcc, exec, s[42:43]
	v_add_f32_e32 v92, 1.0, v92
	s_waitcnt vmcnt(1)
	v_lshlrev_b32_e32 v104, 16, v96
	v_and_b32_e32 v105, 0xffff0000, v96
	s_waitcnt vmcnt(0)
	v_lshlrev_b32_e32 v122, 16, v116
	v_and_b32_e32 v123, 0xffff0000, v116
	v_lshlrev_b32_e32 v96, 16, v97
	v_and_b32_e32 v97, 0xffff0000, v97
	v_lshlrev_b32_e32 v120, 16, v98
	v_and_b32_e32 v121, 0xffff0000, v98
	v_lshlrev_b32_e32 v98, 16, v99
	v_and_b32_e32 v99, 0xffff0000, v99
	v_lshlrev_b32_e32 v110, 16, v117
	v_and_b32_e32 v111, 0xffff0000, v117
	v_lshlrev_b32_e32 v126, 16, v118
	v_and_b32_e32 v127, 0xffff0000, v118
	v_lshlrev_b32_e32 v116, 16, v119
	v_and_b32_e32 v117, 0xffff0000, v119
	v_pk_add_f32 v[118:119], v[104:105], v[122:123]
	v_lshl_add_u64 v[104:105], s[18:19], 0, v[106:107]
	v_pk_add_f32 v[110:111], v[96:97], v[110:111]
	v_pk_add_f32 v[116:117], v[98:99], v[116:117]
	global_load_dwordx4 v[96:99], v[104:105], off nt
	v_rcp_f32_e32 v122, v88
	v_mul_f32_e32 v88, v93, v124
	v_mul_f32_e32 v88, 0xbfb8aa3b, v88
	v_exp_f32_e32 v88, v88
	v_rcp_f32_e32 v123, v92
	v_pk_add_f32 v[120:121], v[120:121], v[126:127]
	v_add_f32_e32 v88, 1.0, v88
	v_rcp_f32_e32 v93, v88
	v_mul_f32_e32 v88, v89, v124
	v_mul_f32_e32 v88, 0xbfb8aa3b, v88
	v_exp_f32_e32 v88, v88
	s_waitcnt vmcnt(0)
	v_and_b32_e32 v127, 0xffff0000, v96
	v_add_f32_e32 v88, 1.0, v88
	v_rcp_f32_e32 v92, v88
	v_mul_f32_e32 v88, v94, v124
	v_mul_f32_e32 v88, 0xbfb8aa3b, v88
	v_exp_f32_e32 v88, v88
	v_and_b32_e32 v126, 0xffff0000, v98
	v_lshlrev_b32_e32 v128, 16, v99
	v_lshlrev_b32_e32 v129, 16, v97
	v_add_f32_e32 v88, 1.0, v88
	v_rcp_f32_e32 v89, v88
	v_mul_f32_e32 v88, v90, v124
	v_mul_f32_e32 v90, v95, v124
	v_mul_f32_e32 v90, 0xbfb8aa3b, v90
	v_exp_f32_e32 v90, v90
	v_mul_f32_e32 v88, 0xbfb8aa3b, v88
	v_exp_f32_e32 v88, v88
	v_and_b32_e32 v97, 0xffff0000, v97
	v_add_f32_e32 v90, 1.0, v90
	v_rcp_f32_e32 v95, v90
	v_mul_f32_e32 v90, v91, v124
	v_mul_f32_e32 v90, 0xbfb8aa3b, v90
	v_exp_f32_e32 v90, v90
	v_add_f32_e32 v88, 1.0, v88
	v_rcp_f32_e32 v88, v88
	v_lshlrev_b32_e32 v91, 16, v96
	v_add_f32_e32 v90, 1.0, v90
	v_rcp_f32_e32 v94, v90
	v_lshlrev_b32_e32 v90, 16, v98
	v_and_b32_e32 v96, 0xffff0000, v99
	v_mov_b32_e32 v98, v120
	v_mov_b32_e32 v99, v118
	v_pk_fma_f32 v[98:99], v[122:123], v[90:91], v[98:99]
	v_mov_b32_e32 v118, v121
	v_mov_b32_e32 v90, v116
	v_mov_b32_e32 v91, v110
	v_mov_b32_e32 v110, v117
	v_pk_fma_f32 v[118:119], v[92:93], v[126:127], v[118:119]
	v_pk_fma_f32 v[120:121], v[88:89], v[128:129], v[90:91]
	v_pk_fma_f32 v[110:111], v[94:95], v[96:97], v[110:111]
	v_lshl_add_u64 v[96:97], v[108:109], 2, s[20:21]
	s_cbranch_vccnz .LBB0_1494
	v_mov_b32_e32 v88, v99
	v_mov_b32_e32 v89, v119
	v_mov_b32_e32 v90, v121
	v_mov_b32_e32 v91, v111
	s_mov_b64 s[4:5], 0
	v_mov_b32_e32 v92, v98
	v_mov_b32_e32 v93, v118
	v_mov_b32_e32 v94, v120
	v_mov_b32_e32 v95, v110
	global_store_dwordx4 v[96:97], v[88:91], off
	global_store_dwordx4 v[96:97], v[92:95], off offset:16

; __device__ __forceinline__ float sigmoidf_(float x) { return __builtin_amdgcn_rcpf(1.f + fexp2(-1.4426950408889634f * x)); }
;     __device__ __forceinline__ void operator()(accv (&acc)[2][2][4][2], const pg8::Unit& u, int wr, int wc, int fr, int fq) const {
;     ...
;                 for (int bj = 0; bj < 2; ++bj) {
;                     const size_t off = (size_t)row * D + col0 + 128 * bj;
;                     const F8 x1 = split_load8(xhi, xlo, off); f32x4 pa, pb4; unpack8(*(const v4u*)(proj + off), pa, pb4);
;                     const accv a0 = acc[ai][bj][m][0] * rs[ai][m], a1 = acc[ai][bj][m][1] * rs[ai][m];
;                     F8 v;
; #pragma unroll
;                     for (int i = 0; i < 4; ++i) { v.a[i] = x1.a[i] + sigmoidf_(a0[i]) * pa[i]; v.b[i] = x1.b[i] + sigmoidf_(a1[i]) * pb4[i]; }
;                     if (outf) { *(f32x4*)(outf + off) = v.a; *(f32x4*)(outf + off + 4) = v.b; }
.LBB0_1496:
	global_load_dwordx4 v[88:91], v[100:101], off offset:256 nt
	s_nop 0
	global_load_dwordx4 v[98:101], v[102:103], off offset:256 nt
	v_mul_f32_e32 v80, v80, v124
	v_mul_f32_e32 v84, v84, v124
	v_mul_f32_e32 v80, 0xbfb8aa3b, v80
	v_mul_f32_e32 v82, v82, v124
	v_mul_f32_e32 v84, 0xbfb8aa3b, v84
	v_exp_f32_e32 v80, v80
	v_mul_f32_e32 v82, 0xbfb8aa3b, v82
	v_exp_f32_e32 v84, v84
	v_exp_f32_e32 v82, v82
	v_add_f32_e32 v80, 1.0, v80
	v_mul_f32_e32 v81, v81, v124
	v_add_f32_e32 v84, 1.0, v84
	v_add_f32_e32 v82, 1.0, v82
	v_mul_f32_e32 v81, 0xbfb8aa3b, v81
	v_mul_f32_e32 v83, v83, v124
	v_exp_f32_e32 v81, v81
	v_mul_f32_e32 v83, 0xbfb8aa3b, v83
	v_exp_f32_e32 v83, v83
	s_mov_b64 s[4:5], -1
	v_add_f32_e32 v81, 1.0, v81
	v_rcp_f32_e32 v81, v81
	v_add_f32_e32 v83, 1.0, v83
	v_rcp_f32_e32 v83, v83
	s_and_b64 vcc, exec, s[42:43]
	s_waitcnt vmcnt(1)
	v_lshlrev_b32_e32 v102, 16, v88
	v_and_b32_e32 v103, 0xffff0000, v88
	v_lshlrev_b32_e32 v88, 16, v89
	v_and_b32_e32 v89, 0xffff0000, v89
	v_lshlrev_b32_e32 v106, 16, v90
	v_and_b32_e32 v107, 0xffff0000, v90
	v_lshlrev_b32_e32 v90, 16, v91
	v_and_b32_e32 v91, 0xffff0000, v91
	s_waitcnt vmcnt(0)
	v_lshlrev_b32_e32 v110, 16, v98
	v_and_b32_e32 v111, 0xffff0000, v98
	v_lshlrev_b32_e32 v98, 16, v99
	v_and_b32_e32 v99, 0xffff0000, v99
	v_lshlrev_b32_e32 v118, 16, v101
	v_and_b32_e32 v119, 0xffff0000, v101
	v_lshlrev_b32_e32 v116, 16, v100
	v_and_b32_e32 v117, 0xffff0000, v100
	v_pk_add_f32 v[100:101], v[88:89], v[98:99]
	v_pk_add_f32 v[98:99], v[90:91], v[118:119]
	global_load_dwordx4 v[88:91], v[104:105], off offset:256 nt
	v_rcp_f32_e32 v105, v80
	v_mul_f32_e32 v80, v85, v124
	v_rcp_f32_e32 v104, v84
	v_mul_f32_e32 v80, 0xbfb8aa3b, v80
	v_mul_f32_e32 v84, v86, v124
	v_rcp_f32_e32 v85, v82
	v_mul_f32_e32 v82, v87, v124
	v_exp_f32_e32 v80, v80
	v_mul_f32_e32 v84, 0xbfb8aa3b, v84
	v_mul_f32_e32 v82, 0xbfb8aa3b, v82
	v_exp_f32_e32 v84, v84
	v_exp_f32_e32 v82, v82
	v_add_f32_e32 v80, 1.0, v80
	v_rcp_f32_e32 v80, v80
	v_add_f32_e32 v84, 1.0, v84
	v_add_f32_e32 v82, 1.0, v82
	v_rcp_f32_e32 v84, v84
	v_rcp_f32_e32 v82, v82
	v_pk_add_f32 v[102:103], v[102:103], v[110:111]
	v_pk_add_f32 v[106:107], v[106:107], v[116:117]
	s_waitcnt vmcnt(0)
	v_and_b32_e32 v111, 0xffff0000, v90
	v_and_b32_e32 v110, 0xffff0000, v88
	v_lshlrev_b32_e32 v116, 16, v89
	v_and_b32_e32 v118, 0xffff0000, v89
	v_mov_b32_e32 v89, v106
	v_mov_b32_e32 v106, v103
	v_lshlrev_b32_e32 v87, 16, v90
	v_lshlrev_b32_e32 v86, 16, v88
	v_lshlrev_b32_e32 v117, 16, v91
	v_and_b32_e32 v119, 0xffff0000, v91
	v_mov_b32_e32 v88, v102
	v_pk_fma_f32 v[90:91], v[80:81], v[110:111], v[106:107]
	v_mov_b32_e32 v80, v100
	v_mov_b32_e32 v81, v98
	v_mov_b32_e32 v98, v101
	v_pk_fma_f32 v[88:89], v[104:105], v[86:87], v[88:89]
	v_pk_fma_f32 v[102:103], v[84:85], v[116:117], v[80:81]
	v_pk_fma_f32 v[98:99], v[82:83], v[118:119], v[98:99]
	s_cbranch_vccnz .LBB0_1499
	v_mov_b32_e32 v80, v88
	v_mov_b32_e32 v81, v90
	v_mov_b32_e32 v82, v102
	v_mov_b32_e32 v83, v98
	v_mov_b32_e32 v84, v89
	v_mov_b32_e32 v85, v91
	v_mov_b32_e32 v86, v103
	v_mov_b32_e32 v87, v99
	global_store_dwordx4 v[96:97], v[80:83], off offset:512
	global_store_dwordx4 v[96:97], v[84:87], off offset:528
	s_cbranch_execz .LBB0_1500

; __device__ __forceinline__ float sigmoidf_(float x) { return __builtin_amdgcn_rcpf(1.f + fexp2(-1.4426950408889634f * x)); }
;     __device__ __forceinline__ void operator()(accv (&acc)[2][2][4][2], const pg8::Unit& u, int wr, int wc, int fr, int fq) const {
;     ...
;                 for (int bj = 0; bj < 2; ++bj) {
;                     const size_t off = (size_t)row * D + col0 + 128 * bj;
;                     const F8 x1 = split_load8(xhi, xlo, off); f32x4 pa, pb4; unpack8(*(const v4u*)(proj + off), pa, pb4);
;                     const accv a0 = acc[ai][bj][m][0] * rs[ai][m], a1 = acc[ai][bj][m][1] * rs[ai][m];
;                     F8 v;
; #pragma unroll
;                     for (int i = 0; i < 4; ++i) { v.a[i] = x1.a[i] + sigmoidf_(a0[i]) * pa[i]; v.b[i] = x1.b[i] + sigmoidf_(a1[i]) * pb4[i]; }
;                     if (outf) { *(f32x4*)(outf + off) = v.a; *(f32x4*)(outf + off + 4) = v.b; }
.LBB0_1504:
	v_add_f32_e32 v80, v216, v217
	v_fmamk_f32 v80, v80, 0x3a800000, v237
	v_rsq_f32_e32 v104, v80
	v_lshlrev_b64 v[80:81], 10, v[164:165]
	v_lshl_add_u64 v[92:93], v[80:81], 0, v[146:147]
	v_lshlrev_b64 v[90:91], 1, v[92:93]
	v_lshl_add_u64 v[84:85], s[2:3], 0, v[90:91]
	v_lshl_add_u64 v[86:87], s[10:11], 0, v[90:91]
	global_load_dwordx4 v[80:83], v[84:85], off nt
	global_load_dwordx4 v[94:97], v[86:87], off nt
	v_mul_f32_e32 v72, v72, v104
	v_mul_f32_e32 v72, 0xbfb8aa3b, v72
	v_exp_f32_e32 v72, v72
	v_mul_f32_e32 v76, v76, v104
	v_mul_f32_e32 v76, 0xbfb8aa3b, v76
	v_exp_f32_e32 v76, v76
	v_add_f32_e32 v72, 1.0, v72
	s_mov_b64 s[4:5], -1
	s_and_b64 vcc, exec, s[42:43]
	v_add_f32_e32 v76, 1.0, v76
	s_waitcnt vmcnt(1)
	v_lshlrev_b32_e32 v88, 16, v80
	v_and_b32_e32 v89, 0xffff0000, v80
	s_waitcnt vmcnt(0)
	v_lshlrev_b32_e32 v98, 16, v94
	v_and_b32_e32 v99, 0xffff0000, v94
	v_lshlrev_b32_e32 v80, 16, v81
	v_and_b32_e32 v81, 0xffff0000, v81
	v_lshlrev_b32_e32 v100, 16, v82
	v_and_b32_e32 v101, 0xffff0000, v82
	v_lshlrev_b32_e32 v82, 16, v83
	v_and_b32_e32 v83, 0xffff0000, v83
	v_lshlrev_b32_e32 v94, 16, v95
	v_and_b32_e32 v95, 0xffff0000, v95
	v_lshlrev_b32_e32 v102, 16, v96
	v_and_b32_e32 v103, 0xffff0000, v96
	v_lshlrev_b32_e32 v96, 16, v97
	v_and_b32_e32 v97, 0xffff0000, v97
	v_pk_add_f32 v[98:99], v[88:89], v[98:99]
	v_lshl_add_u64 v[88:89], s[18:19], 0, v[90:91]
	v_pk_add_f32 v[94:95], v[80:81], v[94:95]
	v_pk_add_f32 v[96:97], v[82:83], v[96:97]
	global_load_dwordx4 v[80:83], v[88:89], off nt
	v_pk_add_f32 v[100:101], v[100:101], v[102:103]
	v_rcp_f32_e32 v102, v72
	v_mul_f32_e32 v72, v77, v104
	v_mul_f32_e32 v72, 0xbfb8aa3b, v72
	v_exp_f32_e32 v72, v72
	v_rcp_f32_e32 v103, v76
	v_add_f32_e32 v72, 1.0, v72
	v_rcp_f32_e32 v77, v72
	v_mul_f32_e32 v72, v73, v104
	v_mul_f32_e32 v72, 0xbfb8aa3b, v72
	v_exp_f32_e32 v72, v72
	s_waitcnt vmcnt(0)
	v_and_b32_e32 v107, 0xffff0000, v80
	v_add_f32_e32 v72, 1.0, v72
	v_rcp_f32_e32 v76, v72
	v_mul_f32_e32 v72, v78, v104
	v_mul_f32_e32 v72, 0xbfb8aa3b, v72
	v_exp_f32_e32 v72, v72
	v_and_b32_e32 v106, 0xffff0000, v82
	v_lshlrev_b32_e32 v108, 16, v83
	v_lshlrev_b32_e32 v109, 16, v81
	v_add_f32_e32 v72, 1.0, v72
	v_rcp_f32_e32 v73, v72
	v_mul_f32_e32 v72, v74, v104
	v_mul_f32_e32 v74, v79, v104
	v_mul_f32_e32 v74, 0xbfb8aa3b, v74
	v_exp_f32_e32 v74, v74
	v_mul_f32_e32 v72, 0xbfb8aa3b, v72
	v_exp_f32_e32 v72, v72
	v_and_b32_e32 v81, 0xffff0000, v81
	v_add_f32_e32 v74, 1.0, v74
	v_rcp_f32_e32 v79, v74
	v_mul_f32_e32 v74, v75, v104
	v_mul_f32_e32 v74, 0xbfb8aa3b, v74
	v_exp_f32_e32 v74, v74
	v_add_f32_e32 v72, 1.0, v72
	v_rcp_f32_e32 v72, v72
	v_lshlrev_b32_e32 v75, 16, v80
	v_add_f32_e32 v74, 1.0, v74
	v_rcp_f32_e32 v78, v74
	v_lshlrev_b32_e32 v74, 16, v82
	v_and_b32_e32 v80, 0xffff0000, v83
	v_mov_b32_e32 v82, v100
	v_mov_b32_e32 v83, v98
	v_pk_fma_f32 v[82:83], v[102:103], v[74:75], v[82:83]
	v_mov_b32_e32 v98, v101
	v_mov_b32_e32 v74, v96
	v_mov_b32_e32 v75, v94
	v_mov_b32_e32 v94, v97
	v_pk_fma_f32 v[98:99], v[76:77], v[106:107], v[98:99]
	v_pk_fma_f32 v[100:101], v[72:73], v[108:109], v[74:75]
	v_pk_fma_f32 v[94:95], v[78:79], v[80:81], v[94:95]
	v_lshl_add_u64 v[80:81], v[92:93], 2, s[20:21]
	s_cbranch_vccnz .LBB0_1506
	v_mov_b32_e32 v72, v83
	v_mov_b32_e32 v73, v99
	v_mov_b32_e32 v74, v101
	v_mov_b32_e32 v75, v95
	s_mov_b64 s[4:5], 0
	v_mov_b32_e32 v76, v82
	v_mov_b32_e32 v77, v98
	v_mov_b32_e32 v78, v100
	v_mov_b32_e32 v79, v94
	global_store_dwordx4 v[80:81], v[72:75], off
	global_store_dwordx4 v[80:81], v[76:79], off offset:16

; __device__ __forceinline__ float sigmoidf_(float x) { return __builtin_amdgcn_rcpf(1.f + fexp2(-1.4426950408889634f * x)); }
;     __device__ __forceinline__ void operator()(accv (&acc)[2][2][4][2], const pg8::Unit& u, int wr, int wc, int fr, int fq) const {
;     ...
;                 for (int bj = 0; bj < 2; ++bj) {
;                     const size_t off = (size_t)row * D + col0 + 128 * bj;
;                     const F8 x1 = split_load8(xhi, xlo, off); f32x4 pa, pb4; unpack8(*(const v4u*)(proj + off), pa, pb4);
;                     const accv a0 = acc[ai][bj][m][0] * rs[ai][m], a1 = acc[ai][bj][m][1] * rs[ai][m];
;                     F8 v;
; #pragma unroll
;                     for (int i = 0; i < 4; ++i) { v.a[i] = x1.a[i] + sigmoidf_(a0[i]) * pa[i]; v.b[i] = x1.b[i] + sigmoidf_(a1[i]) * pb4[i]; }
;                     if (outf) { *(f32x4*)(outf + off) = v.a; *(f32x4*)(outf + off + 4) = v.b; }
.LBB0_1508:
	global_load_dwordx4 v[72:75], v[84:85], off offset:256 nt
	s_nop 0
	global_load_dwordx4 v[82:85], v[86:87], off offset:256 nt
	v_mul_f32_e32 v64, v64, v104
	v_mul_f32_e32 v68, v68, v104
	v_mul_f32_e32 v64, 0xbfb8aa3b, v64
	v_mul_f32_e32 v66, v66, v104
	v_mul_f32_e32 v68, 0xbfb8aa3b, v68
	v_exp_f32_e32 v64, v64
	v_mul_f32_e32 v66, 0xbfb8aa3b, v66
	v_exp_f32_e32 v68, v68
	v_exp_f32_e32 v66, v66
	v_add_f32_e32 v64, 1.0, v64
	v_mul_f32_e32 v65, v65, v104
	v_add_f32_e32 v68, 1.0, v68
	v_add_f32_e32 v66, 1.0, v66
	v_mul_f32_e32 v65, 0xbfb8aa3b, v65
	v_mul_f32_e32 v67, v67, v104
	v_exp_f32_e32 v65, v65
	v_mul_f32_e32 v67, 0xbfb8aa3b, v67
	v_exp_f32_e32 v67, v67
	s_mov_b64 s[4:5], -1
	v_add_f32_e32 v65, 1.0, v65
	v_rcp_f32_e32 v65, v65
	v_add_f32_e32 v67, 1.0, v67
	v_rcp_f32_e32 v67, v67
	s_and_b64 vcc, exec, s[42:43]
	s_waitcnt vmcnt(1)
	v_lshlrev_b32_e32 v86, 16, v72
	v_and_b32_e32 v87, 0xffff0000, v72
	v_lshlrev_b32_e32 v72, 16, v73
	v_and_b32_e32 v73, 0xffff0000, v73
	v_lshlrev_b32_e32 v90, 16, v74
	v_and_b32_e32 v91, 0xffff0000, v74
	v_lshlrev_b32_e32 v74, 16, v75
	v_and_b32_e32 v75, 0xffff0000, v75
	s_waitcnt vmcnt(0)
	v_lshlrev_b32_e32 v94, 16, v82
	v_and_b32_e32 v95, 0xffff0000, v82
	v_lshlrev_b32_e32 v82, 16, v83
	v_and_b32_e32 v83, 0xffff0000, v83
	v_lshlrev_b32_e32 v98, 16, v85
	v_and_b32_e32 v99, 0xffff0000, v85
	v_lshlrev_b32_e32 v96, 16, v84
	v_and_b32_e32 v97, 0xffff0000, v84
	v_pk_add_f32 v[84:85], v[72:73], v[82:83]
	v_pk_add_f32 v[82:83], v[74:75], v[98:99]
	global_load_dwordx4 v[72:75], v[88:89], off offset:256 nt
	v_rcp_f32_e32 v89, v64
	v_mul_f32_e32 v64, v69, v104
	v_rcp_f32_e32 v88, v68
	v_mul_f32_e32 v64, 0xbfb8aa3b, v64
	v_mul_f32_e32 v68, v70, v104
	v_rcp_f32_e32 v69, v66
	v_mul_f32_e32 v66, v71, v104
	v_exp_f32_e32 v64, v64
	v_mul_f32_e32 v68, 0xbfb8aa3b, v68
	v_mul_f32_e32 v66, 0xbfb8aa3b, v66
	v_exp_f32_e32 v68, v68
	v_exp_f32_e32 v66, v66
	v_add_f32_e32 v64, 1.0, v64
	v_rcp_f32_e32 v64, v64
	v_add_f32_e32 v68, 1.0, v68
	v_add_f32_e32 v66, 1.0, v66
	v_rcp_f32_e32 v68, v68
	v_rcp_f32_e32 v66, v66
	v_pk_add_f32 v[86:87], v[86:87], v[94:95]
	v_pk_add_f32 v[90:91], v[90:91], v[96:97]
	s_waitcnt vmcnt(0)
	v_and_b32_e32 v95, 0xffff0000, v74
	v_and_b32_e32 v94, 0xffff0000, v72
	v_lshlrev_b32_e32 v96, 16, v73
	v_and_b32_e32 v98, 0xffff0000, v73
	v_mov_b32_e32 v73, v90
	v_mov_b32_e32 v90, v87
	v_lshlrev_b32_e32 v71, 16, v74
	v_lshlrev_b32_e32 v70, 16, v72
	v_lshlrev_b32_e32 v97, 16, v75
	v_and_b32_e32 v99, 0xffff0000, v75
	v_mov_b32_e32 v72, v86
	v_pk_fma_f32 v[74:75], v[64:65], v[94:95], v[90:91]
	v_mov_b32_e32 v64, v84
	v_mov_b32_e32 v65, v82
	v_mov_b32_e32 v82, v85
	v_pk_fma_f32 v[72:73], v[88:89], v[70:71], v[72:73]
	v_pk_fma_f32 v[86:87], v[68:69], v[96:97], v[64:65]
	v_pk_fma_f32 v[82:83], v[66:67], v[98:99], v[82:83]
	s_cbranch_vccnz .LBB0_1511
	v_mov_b32_e32 v64, v72
	v_mov_b32_e32 v65, v74
	v_mov_b32_e32 v66, v86
	v_mov_b32_e32 v67, v82
	v_mov_b32_e32 v68, v73
	v_mov_b32_e32 v69, v75
	v_mov_b32_e32 v70, v87
	v_mov_b32_e32 v71, v83
	global_store_dwordx4 v[80:81], v[64:67], off offset:512
	global_store_dwordx4 v[80:81], v[68:71], off offset:528
	s_cbranch_execz .LBB0_1512

; __device__ __forceinline__ float sigmoidf_(float x) { return __builtin_amdgcn_rcpf(1.f + fexp2(-1.4426950408889634f * x)); }
;     __device__ __forceinline__ void operator()(accv (&acc)[2][2][4][2], const pg8::Unit& u, int wr, int wc, int fr, int fq) const {
;     ...
;                 for (int bj = 0; bj < 2; ++bj) {
;                     const size_t off = (size_t)row * D + col0 + 128 * bj;
;                     const F8 x1 = split_load8(xhi, xlo, off); f32x4 pa, pb4; unpack8(*(const v4u*)(proj + off), pa, pb4);
;                     const accv a0 = acc[ai][bj][m][0] * rs[ai][m], a1 = acc[ai][bj][m][1] * rs[ai][m];
;                     F8 v;
; #pragma unroll
;                     for (int i = 0; i < 4; ++i) { v.a[i] = x1.a[i] + sigmoidf_(a0[i]) * pa[i]; v.b[i] = x1.b[i] + sigmoidf_(a1[i]) * pb4[i]; }
;                     if (outf) { *(f32x4*)(outf + off) = v.a; *(f32x4*)(outf + off + 4) = v.b; }
.LBB0_1516:
	v_add_f32_e32 v64, v214, v215
	v_fmamk_f32 v64, v64, 0x3a800000, v237
	v_rsq_f32_e32 v88, v64
	v_lshlrev_b64 v[64:65], 10, v[160:161]
	v_lshl_add_u64 v[76:77], v[64:65], 0, v[146:147]
	v_lshlrev_b64 v[74:75], 1, v[76:77]
	v_lshl_add_u64 v[68:69], s[2:3], 0, v[74:75]
	v_lshl_add_u64 v[70:71], s[10:11], 0, v[74:75]
	global_load_dwordx4 v[64:67], v[68:69], off nt
	global_load_dwordx4 v[78:81], v[70:71], off nt
	v_mul_f32_e32 v56, v56, v88
	v_mul_f32_e32 v60, v60, v88
	v_mul_f32_e32 v56, 0xbfb8aa3b, v56
	v_mul_f32_e32 v58, v58, v88
	v_mul_f32_e32 v60, 0xbfb8aa3b, v60
	v_exp_f32_e32 v56, v56
	v_mul_f32_e32 v58, 0xbfb8aa3b, v58
	v_exp_f32_e32 v60, v60
	v_exp_f32_e32 v58, v58
	v_add_f32_e32 v56, 1.0, v56
	v_mul_f32_e32 v57, v57, v88
	v_add_f32_e32 v60, 1.0, v60
	v_add_f32_e32 v58, 1.0, v58
	v_mul_f32_e32 v57, 0xbfb8aa3b, v57
	v_mul_f32_e32 v59, v59, v88
	v_exp_f32_e32 v57, v57
	v_mul_f32_e32 v59, 0xbfb8aa3b, v59
	v_exp_f32_e32 v59, v59
	s_mov_b64 s[4:5], -1
	v_add_f32_e32 v57, 1.0, v57
	v_rcp_f32_e32 v57, v57
	v_add_f32_e32 v59, 1.0, v59
	v_rcp_f32_e32 v59, v59
	s_and_b64 vcc, exec, s[42:43]
	s_waitcnt vmcnt(1)
	v_lshlrev_b32_e32 v72, 16, v64
	v_and_b32_e32 v73, 0xffff0000, v64
	s_waitcnt vmcnt(0)
	v_lshlrev_b32_e32 v82, 16, v78
	v_and_b32_e32 v83, 0xffff0000, v78
	v_lshlrev_b32_e32 v64, 16, v65
	v_and_b32_e32 v65, 0xffff0000, v65
	v_lshlrev_b32_e32 v84, 16, v66
	v_and_b32_e32 v85, 0xffff0000, v66
	v_lshlrev_b32_e32 v66, 16, v67
	v_and_b32_e32 v67, 0xffff0000, v67
	v_lshlrev_b32_e32 v78, 16, v79
	v_and_b32_e32 v79, 0xffff0000, v79
	v_lshlrev_b32_e32 v86, 16, v80
	v_and_b32_e32 v87, 0xffff0000, v80
	v_lshlrev_b32_e32 v80, 16, v81
	v_and_b32_e32 v81, 0xffff0000, v81
	v_pk_add_f32 v[82:83], v[72:73], v[82:83]
	v_lshl_add_u64 v[72:73], s[18:19], 0, v[74:75]
	v_pk_add_f32 v[78:79], v[64:65], v[78:79]
	v_pk_add_f32 v[80:81], v[66:67], v[80:81]
	global_load_dwordx4 v[64:67], v[72:73], off nt
	v_pk_add_f32 v[84:85], v[84:85], v[86:87]
	v_rcp_f32_e32 v87, v56
	v_mul_f32_e32 v56, v61, v88
	v_rcp_f32_e32 v86, v60
	v_mul_f32_e32 v56, 0xbfb8aa3b, v56
	v_mul_f32_e32 v60, v62, v88
	v_rcp_f32_e32 v61, v58
	v_mul_f32_e32 v58, v63, v88
	v_exp_f32_e32 v56, v56
	v_mul_f32_e32 v60, 0xbfb8aa3b, v60
	v_mul_f32_e32 v58, 0xbfb8aa3b, v58
	v_exp_f32_e32 v60, v60
	v_exp_f32_e32 v58, v58
	v_add_f32_e32 v56, 1.0, v56
	v_rcp_f32_e32 v56, v56
	v_add_f32_e32 v60, 1.0, v60
	v_add_f32_e32 v58, 1.0, v58
	v_rcp_f32_e32 v60, v60
	v_rcp_f32_e32 v58, v58
	s_waitcnt vmcnt(0)
	v_and_b32_e32 v91, 0xffff0000, v66
	v_and_b32_e32 v90, 0xffff0000, v64
	v_lshlrev_b32_e32 v92, 16, v65
	v_and_b32_e32 v94, 0xffff0000, v65
	v_mov_b32_e32 v65, v84
	v_mov_b32_e32 v84, v83
	v_lshlrev_b32_e32 v63, 16, v66
	v_lshlrev_b32_e32 v62, 16, v64
	v_lshlrev_b32_e32 v93, 16, v67
	v_and_b32_e32 v95, 0xffff0000, v67
	v_mov_b32_e32 v64, v82
	v_pk_fma_f32 v[82:83], v[56:57], v[90:91], v[84:85]
	v_mov_b32_e32 v56, v78
	v_mov_b32_e32 v57, v80
	v_mov_b32_e32 v80, v79
	v_pk_fma_f32 v[66:67], v[86:87], v[62:63], v[64:65]
	v_pk_fma_f32 v[84:85], v[60:61], v[92:93], v[56:57]
	v_pk_fma_f32 v[78:79], v[58:59], v[94:95], v[80:81]
	v_lshl_add_u64 v[64:65], v[76:77], 2, s[20:21]
	s_cbranch_vccnz .LBB0_1518
	v_mov_b32_e32 v56, v66
	v_mov_b32_e32 v57, v82
	v_mov_b32_e32 v58, v84
	v_mov_b32_e32 v59, v78
	s_mov_b64 s[4:5], 0
	v_mov_b32_e32 v60, v67
	v_mov_b32_e32 v61, v83
	v_mov_b32_e32 v62, v85
	v_mov_b32_e32 v63, v79
	global_store_dwordx4 v[64:65], v[56:59], off
	global_store_dwordx4 v[64:65], v[60:63], off offset:16

; __device__ __forceinline__ float sigmoidf_(float x) { return __builtin_amdgcn_rcpf(1.f + fexp2(-1.4426950408889634f * x)); }
;     __device__ __forceinline__ void operator()(accv (&acc)[2][2][4][2], const pg8::Unit& u, int wr, int wc, int fr, int fq) const {
;     ...
;                 for (int bj = 0; bj < 2; ++bj) {
;                     const size_t off = (size_t)row * D + col0 + 128 * bj;
;                     const F8 x1 = split_load8(xhi, xlo, off); f32x4 pa, pb4; unpack8(*(const v4u*)(proj + off), pa, pb4);
;                     const accv a0 = acc[ai][bj][m][0] * rs[ai][m], a1 = acc[ai][bj][m][1] * rs[ai][m];
;                     F8 v;
; #pragma unroll
;                     for (int i = 0; i < 4; ++i) { v.a[i] = x1.a[i] + sigmoidf_(a0[i]) * pa[i]; v.b[i] = x1.b[i] + sigmoidf_(a1[i]) * pb4[i]; }
;                     if (outf) { *(f32x4*)(outf + off) = v.a; *(f32x4*)(outf + off + 4) = v.b; }
.LBB0_1520:
	global_load_dwordx4 v[56:59], v[68:69], off offset:256 nt
	s_nop 0
	global_load_dwordx4 v[66:69], v[70:71], off offset:256 nt
	v_mul_f32_e32 v48, v48, v88
	v_mul_f32_e32 v52, v52, v88
	v_mul_f32_e32 v48, 0xbfb8aa3b, v48
	v_mul_f32_e32 v50, v50, v88
	v_mul_f32_e32 v52, 0xbfb8aa3b, v52
	v_exp_f32_e32 v48, v48
	v_mul_f32_e32 v50, 0xbfb8aa3b, v50
	v_exp_f32_e32 v52, v52
	v_exp_f32_e32 v50, v50
	v_add_f32_e32 v48, 1.0, v48
	v_mul_f32_e32 v49, v49, v88
	v_add_f32_e32 v52, 1.0, v52
	v_add_f32_e32 v50, 1.0, v50
	v_mul_f32_e32 v49, 0xbfb8aa3b, v49
	v_mul_f32_e32 v51, v51, v88
	v_exp_f32_e32 v49, v49
	v_mul_f32_e32 v51, 0xbfb8aa3b, v51
	v_exp_f32_e32 v51, v51
	s_mov_b64 s[4:5], -1
	v_add_f32_e32 v49, 1.0, v49
	v_rcp_f32_e32 v49, v49
	v_add_f32_e32 v51, 1.0, v51
	v_rcp_f32_e32 v51, v51
	s_and_b64 vcc, exec, s[42:43]
	s_waitcnt vmcnt(1)
	v_lshlrev_b32_e32 v70, 16, v56
	v_and_b32_e32 v71, 0xffff0000, v56
	v_lshlrev_b32_e32 v56, 16, v57
	v_and_b32_e32 v57, 0xffff0000, v57
	v_lshlrev_b32_e32 v74, 16, v58
	v_and_b32_e32 v75, 0xffff0000, v58
	v_lshlrev_b32_e32 v58, 16, v59
	v_and_b32_e32 v59, 0xffff0000, v59
	s_waitcnt vmcnt(0)
	v_lshlrev_b32_e32 v78, 16, v66
	v_and_b32_e32 v79, 0xffff0000, v66
	v_lshlrev_b32_e32 v66, 16, v67
	v_and_b32_e32 v67, 0xffff0000, v67
	v_lshlrev_b32_e32 v82, 16, v69
	v_and_b32_e32 v83, 0xffff0000, v69
	v_lshlrev_b32_e32 v80, 16, v68
	v_and_b32_e32 v81, 0xffff0000, v68
	v_pk_add_f32 v[68:69], v[56:57], v[66:67]
	v_pk_add_f32 v[66:67], v[58:59], v[82:83]
	global_load_dwordx4 v[56:59], v[72:73], off offset:256 nt
	v_rcp_f32_e32 v73, v48
	v_mul_f32_e32 v48, v53, v88
	v_rcp_f32_e32 v72, v52
	v_mul_f32_e32 v48, 0xbfb8aa3b, v48
	v_mul_f32_e32 v52, v54, v88
	v_rcp_f32_e32 v53, v50
	v_mul_f32_e32 v50, v55, v88
	v_exp_f32_e32 v48, v48
	v_mul_f32_e32 v52, 0xbfb8aa3b, v52
	v_mul_f32_e32 v50, 0xbfb8aa3b, v50
	v_exp_f32_e32 v52, v52
	v_exp_f32_e32 v50, v50
	v_add_f32_e32 v48, 1.0, v48
	v_rcp_f32_e32 v48, v48
	v_add_f32_e32 v52, 1.0, v52
	v_add_f32_e32 v50, 1.0, v50
	v_rcp_f32_e32 v52, v52
	v_rcp_f32_e32 v50, v50
	v_pk_add_f32 v[70:71], v[70:71], v[78:79]
	v_pk_add_f32 v[74:75], v[74:75], v[80:81]
	s_waitcnt vmcnt(0)
	v_and_b32_e32 v79, 0xffff0000, v58
	v_and_b32_e32 v78, 0xffff0000, v56
	v_lshlrev_b32_e32 v80, 16, v57
	v_and_b32_e32 v82, 0xffff0000, v57
	v_mov_b32_e32 v57, v74
	v_mov_b32_e32 v74, v71
	v_lshlrev_b32_e32 v55, 16, v58
	v_lshlrev_b32_e32 v54, 16, v56
	v_lshlrev_b32_e32 v81, 16, v59
	v_and_b32_e32 v83, 0xffff0000, v59
	v_mov_b32_e32 v56, v70
	v_pk_fma_f32 v[58:59], v[48:49], v[78:79], v[74:75]
	v_mov_b32_e32 v48, v68
	v_mov_b32_e32 v49, v66
	v_mov_b32_e32 v66, v69
	v_pk_fma_f32 v[56:57], v[72:73], v[54:55], v[56:57]
	v_pk_fma_f32 v[70:71], v[52:53], v[80:81], v[48:49]
	v_pk_fma_f32 v[66:67], v[50:51], v[82:83], v[66:67]
	s_cbranch_vccnz .LBB0_1523
	v_mov_b32_e32 v48, v56
	v_mov_b32_e32 v49, v58
	v_mov_b32_e32 v50, v70
	v_mov_b32_e32 v51, v66
	v_mov_b32_e32 v52, v57
	v_mov_b32_e32 v53, v59
	v_mov_b32_e32 v54, v71
	v_mov_b32_e32 v55, v67
	global_store_dwordx4 v[64:65], v[48:51], off offset:512
	global_store_dwordx4 v[64:65], v[52:55], off offset:528
	s_cbranch_execz .LBB0_1524

; __device__ __forceinline__ float sigmoidf_(float x) { return __builtin_amdgcn_rcpf(1.f + fexp2(-1.4426950408889634f * x)); }
; __device__ __forceinline__ float swap_sum(float v) { auto rr = __builtin_amdgcn_permlane32_swap(__float_as_uint(v), __float_as_uint(v), false, false); return __uint_as_float(rr[0]) + __uint_as_float(rr[1]); }
; __device__ __forceinline__ void load_rstd(const float* ss, int rowb, int fq, float (&rs)[2][4]) {
;     ...
;             rs[ai][m] = __builtin_amdgcn_rsqf(s * (1.0f / D) + EPS);
;     __device__ __forceinline__ void operator()(accv (&acc)[2][2][4][2], const pg8::Unit& u, int wr, int wc, int fr, int fq) const {
;     ...
;                 const int row = rowb + 128 * ai + 16 * m; float s = 0.f;
; #pragma unroll
;                 for (int bj = 0; bj < 2; ++bj) {
;                     const size_t off = (size_t)row * D + col0 + 128 * bj;
;                     const F8 x1 = split_load8(xhi, xlo, off); f32x4 pa, pb4; unpack8(*(const v4u*)(proj + off), pa, pb4);
;                     const accv a0 = acc[ai][bj][m][0] * rs[ai][m], a1 = acc[ai][bj][m][1] * rs[ai][m];
;                     F8 v;
; #pragma unroll
;                     for (int i = 0; i < 4; ++i) { v.a[i] = x1.a[i] + sigmoidf_(a0[i]) * pa[i]; v.b[i] = x1.b[i] + sigmoidf_(a1[i]) * pb4[i]; }
;                     if (outf) { *(f32x4*)(outf + off) = v.a; *(f32x4*)(outf + off + 4) = v.b; }
;                     else { split_store8(ohi, olo, off, v);
;                         s += ((v.a[0] * v.a[0] + v.a[1] * v.a[1]) + (v.a[2] * v.a[2] + v.a[3] * v.a[3])) + ((v.b[0] * v.b[0] + v.b[1] * v.b[1]) + (v.b[2] * v.b[2] + v.b[3] * v.b[3])); }
;                 }
;                 if (!outf) { s += xshfl<16>(s); s = swap_sum(s); if (fq == 0) ssout[(size_t)row * 16 + u.pn * 4 + wc] = s; }
.LBB0_1528:
	v_add_f32_e32 v48, v212, v213
	v_fmamk_f32 v48, v48, 0x3a800000, v237
	v_rsq_f32_e32 v72, v48
	v_lshlrev_b64 v[48:49], 10, v[156:157]
	v_lshl_add_u64 v[60:61], v[48:49], 0, v[146:147]
	v_lshlrev_b64 v[58:59], 1, v[60:61]
	v_lshl_add_u64 v[52:53], s[2:3], 0, v[58:59]
	v_lshl_add_u64 v[54:55], s[10:11], 0, v[58:59]
	global_load_dwordx4 v[48:51], v[52:53], off nt
	global_load_dwordx4 v[62:65], v[54:55], off nt
	v_mul_f32_e32 v40, v40, v72
	v_mul_f32_e32 v40, 0xbfb8aa3b, v40
	v_exp_f32_e32 v40, v40
	v_mul_f32_e32 v44, v44, v72
	v_mul_f32_e32 v44, 0xbfb8aa3b, v44
	v_exp_f32_e32 v44, v44
	v_add_f32_e32 v40, 1.0, v40
	s_mov_b64 s[4:5], -1
	s_and_b64 vcc, exec, s[42:43]
	v_add_f32_e32 v44, 1.0, v44
	s_waitcnt vmcnt(1)
	v_lshlrev_b32_e32 v56, 16, v48
	v_and_b32_e32 v57, 0xffff0000, v48
	s_waitcnt vmcnt(0)
	v_lshlrev_b32_e32 v66, 16, v62
	v_and_b32_e32 v67, 0xffff0000, v62
	v_lshlrev_b32_e32 v48, 16, v49
	v_and_b32_e32 v49, 0xffff0000, v49
	v_lshlrev_b32_e32 v68, 16, v50
	v_and_b32_e32 v69, 0xffff0000, v50
	v_lshlrev_b32_e32 v50, 16, v51
	v_and_b32_e32 v51, 0xffff0000, v51
	v_lshlrev_b32_e32 v62, 16, v63
	v_and_b32_e32 v63, 0xffff0000, v63
	v_lshlrev_b32_e32 v70, 16, v64
	v_and_b32_e32 v71, 0xffff0000, v64
	v_lshlrev_b32_e32 v64, 16, v65
	v_and_b32_e32 v65, 0xffff0000, v65
	v_pk_add_f32 v[66:67], v[56:57], v[66:67]
	v_lshl_add_u64 v[56:57], s[18:19], 0, v[58:59]
	v_pk_add_f32 v[62:63], v[48:49], v[62:63]
	v_pk_add_f32 v[64:65], v[50:51], v[64:65]
	global_load_dwordx4 v[48:51], v[56:57], off nt
	v_pk_add_f32 v[68:69], v[68:69], v[70:71]
	v_rcp_f32_e32 v70, v40
	v_mul_f32_e32 v40, v45, v72
	v_mul_f32_e32 v40, 0xbfb8aa3b, v40
	v_exp_f32_e32 v40, v40
	v_rcp_f32_e32 v71, v44
	v_add_f32_e32 v40, 1.0, v40
	v_rcp_f32_e32 v45, v40
	v_mul_f32_e32 v40, v41, v72
	v_mul_f32_e32 v40, 0xbfb8aa3b, v40
	v_exp_f32_e32 v40, v40
	s_waitcnt vmcnt(0)
	v_and_b32_e32 v75, 0xffff0000, v48
	v_add_f32_e32 v40, 1.0, v40
	v_rcp_f32_e32 v44, v40
	v_mul_f32_e32 v40, v46, v72
	v_mul_f32_e32 v40, 0xbfb8aa3b, v40
	v_exp_f32_e32 v40, v40
	v_and_b32_e32 v74, 0xffff0000, v50
	v_lshlrev_b32_e32 v76, 16, v51
	v_lshlrev_b32_e32 v77, 16, v49
	v_add_f32_e32 v40, 1.0, v40
	v_rcp_f32_e32 v41, v40
	v_mul_f32_e32 v40, v42, v72
	v_mul_f32_e32 v42, v47, v72
	v_mul_f32_e32 v42, 0xbfb8aa3b, v42
	v_exp_f32_e32 v42, v42
	v_mul_f32_e32 v40, 0xbfb8aa3b, v40
	v_exp_f32_e32 v40, v40
	v_and_b32_e32 v49, 0xffff0000, v49
	v_add_f32_e32 v42, 1.0, v42
	v_rcp_f32_e32 v47, v42
	v_mul_f32_e32 v42, v43, v72
	v_mul_f32_e32 v42, 0xbfb8aa3b, v42
	v_exp_f32_e32 v42, v42
	v_add_f32_e32 v40, 1.0, v40
	v_rcp_f32_e32 v40, v40
	v_lshlrev_b32_e32 v43, 16, v48
	v_add_f32_e32 v42, 1.0, v42
	v_rcp_f32_e32 v46, v42
	v_lshlrev_b32_e32 v42, 16, v50
	v_and_b32_e32 v48, 0xffff0000, v51
	v_mov_b32_e32 v50, v68
	v_mov_b32_e32 v51, v66
	v_pk_fma_f32 v[50:51], v[70:71], v[42:43], v[50:51]
	v_mov_b32_e32 v66, v69
	v_mov_b32_e32 v42, v64
	v_mov_b32_e32 v43, v62
	v_mov_b32_e32 v62, v65
	v_pk_fma_f32 v[66:67], v[44:45], v[74:75], v[66:67]
	v_pk_fma_f32 v[68:69], v[40:41], v[76:77], v[42:43]
	v_pk_fma_f32 v[62:63], v[46:47], v[48:49], v[62:63]
	v_lshl_add_u64 v[48:49], v[60:61], 2, s[20:21]
	s_cbranch_vccnz .LBB0_1530
	v_mov_b32_e32 v40, v51
	v_mov_b32_e32 v41, v67
	v_mov_b32_e32 v42, v69
	v_mov_b32_e32 v43, v63
	s_mov_b64 s[4:5], 0
	v_mov_b32_e32 v44, v50
	v_mov_b32_e32 v45, v66
	v_mov_b32_e32 v46, v68
	v_mov_b32_e32 v47, v62
	global_store_dwordx4 v[48:49], v[40:43], off
	global_store_dwordx4 v[48:49], v[44:47], off offset:16

; __device__ __forceinline__ float sigmoidf_(float x) { return __builtin_amdgcn_rcpf(1.f + fexp2(-1.4426950408889634f * x)); }
;     __device__ __forceinline__ void operator()(accv (&acc)[2][2][4][2], const pg8::Unit& u, int wr, int wc, int fr, int fq) const {
;     ...
;                 for (int bj = 0; bj < 2; ++bj) {
;                     const size_t off = (size_t)row * D + col0 + 128 * bj;
;                     const F8 x1 = split_load8(xhi, xlo, off); f32x4 pa, pb4; unpack8(*(const v4u*)(proj + off), pa, pb4);
;                     const accv a0 = acc[ai][bj][m][0] * rs[ai][m], a1 = acc[ai][bj][m][1] * rs[ai][m];
;                     F8 v;
; #pragma unroll
;                     for (int i = 0; i < 4; ++i) { v.a[i] = x1.a[i] + sigmoidf_(a0[i]) * pa[i]; v.b[i] = x1.b[i] + sigmoidf_(a1[i]) * pb4[i]; }
;                     if (outf) { *(f32x4*)(outf + off) = v.a; *(f32x4*)(outf + off + 4) = v.b; }
;                     else { split_store8(ohi, olo, off, v);
;                         s += ((v.a[0] * v.a[0] + v.a[1] * v.a[1]) + (v.a[2] * v.a[2] + v.a[3] * v.a[3])) + ((v.b[0] * v.b[0] + v.b[1] * v.b[1]) + (v.b[2] * v.b[2] + v.b[3] * v.b[3])); }
.LBB0_1532:
	global_load_dwordx4 v[40:43], v[52:53], off offset:256 nt
	s_nop 0
	global_load_dwordx4 v[50:53], v[54:55], off offset:256 nt
	v_mul_f32_e32 v32, v32, v72
	v_mul_f32_e32 v36, v36, v72
	v_mul_f32_e32 v32, 0xbfb8aa3b, v32
	v_mul_f32_e32 v34, v34, v72
	v_mul_f32_e32 v36, 0xbfb8aa3b, v36
	v_exp_f32_e32 v32, v32
	v_mul_f32_e32 v34, 0xbfb8aa3b, v34
	v_exp_f32_e32 v36, v36
	v_exp_f32_e32 v34, v34
	v_add_f32_e32 v32, 1.0, v32
	v_mul_f32_e32 v33, v33, v72
	v_add_f32_e32 v36, 1.0, v36
	v_add_f32_e32 v34, 1.0, v34
	v_mul_f32_e32 v33, 0xbfb8aa3b, v33
	v_mul_f32_e32 v35, v35, v72
	v_exp_f32_e32 v33, v33
	v_mul_f32_e32 v35, 0xbfb8aa3b, v35
	v_exp_f32_e32 v35, v35
	s_mov_b64 s[4:5], -1
	v_add_f32_e32 v33, 1.0, v33
	v_rcp_f32_e32 v33, v33
	v_add_f32_e32 v35, 1.0, v35
	v_rcp_f32_e32 v35, v35
	s_and_b64 vcc, exec, s[42:43]
	s_waitcnt vmcnt(1)
	v_lshlrev_b32_e32 v54, 16, v40
	v_and_b32_e32 v55, 0xffff0000, v40
	v_lshlrev_b32_e32 v40, 16, v41
	v_and_b32_e32 v41, 0xffff0000, v41
	v_lshlrev_b32_e32 v58, 16, v42
	v_and_b32_e32 v59, 0xffff0000, v42
	v_lshlrev_b32_e32 v42, 16, v43
	v_and_b32_e32 v43, 0xffff0000, v43
	s_waitcnt vmcnt(0)
	v_lshlrev_b32_e32 v62, 16, v50
	v_and_b32_e32 v63, 0xffff0000, v50
	v_lshlrev_b32_e32 v50, 16, v51
	v_and_b32_e32 v51, 0xffff0000, v51
	v_lshlrev_b32_e32 v66, 16, v53
	v_and_b32_e32 v67, 0xffff0000, v53
	v_lshlrev_b32_e32 v64, 16, v52
	v_and_b32_e32 v65, 0xffff0000, v52
	v_pk_add_f32 v[52:53], v[40:41], v[50:51]
	v_pk_add_f32 v[50:51], v[42:43], v[66:67]
	global_load_dwordx4 v[40:43], v[56:57], off offset:256 nt
	v_rcp_f32_e32 v57, v32
	v_mul_f32_e32 v32, v37, v72
	v_rcp_f32_e32 v56, v36
	v_mul_f32_e32 v32, 0xbfb8aa3b, v32
	v_mul_f32_e32 v36, v38, v72
	v_rcp_f32_e32 v37, v34
	v_mul_f32_e32 v34, v39, v72
	v_exp_f32_e32 v32, v32
	v_mul_f32_e32 v36, 0xbfb8aa3b, v36
	v_mul_f32_e32 v34, 0xbfb8aa3b, v34
	v_exp_f32_e32 v36, v36
	v_exp_f32_e32 v34, v34
	v_add_f32_e32 v32, 1.0, v32
	v_rcp_f32_e32 v32, v32
	v_add_f32_e32 v36, 1.0, v36
	v_add_f32_e32 v34, 1.0, v34
	v_rcp_f32_e32 v36, v36
	v_rcp_f32_e32 v34, v34
	v_pk_add_f32 v[54:55], v[54:55], v[62:63]
	v_pk_add_f32 v[58:59], v[58:59], v[64:65]
	s_waitcnt vmcnt(0)
	v_and_b32_e32 v63, 0xffff0000, v42
	v_and_b32_e32 v62, 0xffff0000, v40
	v_lshlrev_b32_e32 v64, 16, v41
	v_and_b32_e32 v66, 0xffff0000, v41
	v_mov_b32_e32 v41, v58
	v_mov_b32_e32 v58, v55
	v_lshlrev_b32_e32 v39, 16, v42
	v_lshlrev_b32_e32 v38, 16, v40
	v_lshlrev_b32_e32 v65, 16, v43
	v_and_b32_e32 v67, 0xffff0000, v43
	v_mov_b32_e32 v40, v54
	v_pk_fma_f32 v[42:43], v[32:33], v[62:63], v[58:59]
	v_mov_b32_e32 v32, v52
	v_mov_b32_e32 v33, v50
	v_mov_b32_e32 v50, v53
	v_pk_fma_f32 v[40:41], v[56:57], v[38:39], v[40:41]
	v_pk_fma_f32 v[54:55], v[36:37], v[64:65], v[32:33]
	v_pk_fma_f32 v[50:51], v[34:35], v[66:67], v[50:51]
	s_cbranch_vccnz .LBB0_1535
	v_mov_b32_e32 v32, v40
	v_mov_b32_e32 v33, v42
	v_mov_b32_e32 v34, v54
	v_mov_b32_e32 v35, v50
	v_mov_b32_e32 v36, v41
	v_mov_b32_e32 v37, v43
	v_mov_b32_e32 v38, v55
	v_mov_b32_e32 v39, v51
	global_store_dwordx4 v[48:49], v[32:35], off offset:512
	global_store_dwordx4 v[48:49], v[36:39], off offset:528
	s_cbranch_execz .LBB0_1536

; __device__ __forceinline__ float sigmoidf_(float x) { return __builtin_amdgcn_rcpf(1.f + fexp2(-1.4426950408889634f * x)); }
; __device__ __forceinline__ float swap_sum(float v) { auto rr = __builtin_amdgcn_permlane32_swap(__float_as_uint(v), __float_as_uint(v), false, false); return __uint_as_float(rr[0]) + __uint_as_float(rr[1]); }
; __device__ __forceinline__ void load_rstd(const float* ss, int rowb, int fq, float (&rs)[2][4]) {
;     ...
;             rs[ai][m] = __builtin_amdgcn_rsqf(s * (1.0f / D) + EPS);
;     __device__ __forceinline__ void operator()(accv (&acc)[2][2][4][2], const pg8::Unit& u, int wr, int wc, int fr, int fq) const {
;     ...
;                 const int row = rowb + 128 * ai + 16 * m; float s = 0.f;
; #pragma unroll
;                 for (int bj = 0; bj < 2; ++bj) {
;                     const size_t off = (size_t)row * D + col0 + 128 * bj;
;                     const F8 x1 = split_load8(xhi, xlo, off); f32x4 pa, pb4; unpack8(*(const v4u*)(proj + off), pa, pb4);
;                     const accv a0 = acc[ai][bj][m][0] * rs[ai][m], a1 = acc[ai][bj][m][1] * rs[ai][m];
;                     F8 v;
; #pragma unroll
;                     for (int i = 0; i < 4; ++i) { v.a[i] = x1.a[i] + sigmoidf_(a0[i]) * pa[i]; v.b[i] = x1.b[i] + sigmoidf_(a1[i]) * pb4[i]; }
;                     if (outf) { *(f32x4*)(outf + off) = v.a; *(f32x4*)(outf + off + 4) = v.b; }
;                     else { split_store8(ohi, olo, off, v);
;                         s += ((v.a[0] * v.a[0] + v.a[1] * v.a[1]) + (v.a[2] * v.a[2] + v.a[3] * v.a[3])) + ((v.b[0] * v.b[0] + v.b[1] * v.b[1]) + (v.b[2] * v.b[2] + v.b[3] * v.b[3])); }
;                 }
;                 if (!outf) { s += xshfl<16>(s); s = swap_sum(s); if (fq == 0) ssout[(size_t)row * 16 + u.pn * 4 + wc] = s; }
.LBB0_1540:
	v_add_f32_e32 v32, v210, v211
	v_fmamk_f32 v32, v32, 0x3a800000, v237
	v_rsq_f32_e32 v56, v32
	v_lshlrev_b64 v[32:33], 10, v[152:153]
	v_lshl_add_u64 v[44:45], v[32:33], 0, v[146:147]
	v_lshlrev_b64 v[42:43], 1, v[44:45]
	v_lshl_add_u64 v[36:37], s[2:3], 0, v[42:43]
	v_lshl_add_u64 v[38:39], s[10:11], 0, v[42:43]
	global_load_dwordx4 v[32:35], v[36:37], off nt
	global_load_dwordx4 v[46:49], v[38:39], off nt
	v_mul_f32_e32 v24, v24, v56
	v_mul_f32_e32 v24, 0xbfb8aa3b, v24
	v_exp_f32_e32 v24, v24
	v_mul_f32_e32 v28, v28, v56
	v_mul_f32_e32 v28, 0xbfb8aa3b, v28
	v_exp_f32_e32 v28, v28
	v_add_f32_e32 v24, 1.0, v24
	s_mov_b64 s[4:5], -1
	s_and_b64 vcc, exec, s[42:43]
	v_add_f32_e32 v28, 1.0, v28
	s_waitcnt vmcnt(1)
	v_lshlrev_b32_e32 v40, 16, v32
	v_and_b32_e32 v41, 0xffff0000, v32
	s_waitcnt vmcnt(0)
	v_lshlrev_b32_e32 v50, 16, v46
	v_and_b32_e32 v51, 0xffff0000, v46
	v_lshlrev_b32_e32 v32, 16, v33
	v_and_b32_e32 v33, 0xffff0000, v33
	v_lshlrev_b32_e32 v52, 16, v34
	v_and_b32_e32 v53, 0xffff0000, v34
	v_lshlrev_b32_e32 v34, 16, v35
	v_and_b32_e32 v35, 0xffff0000, v35
	v_lshlrev_b32_e32 v46, 16, v47
	v_and_b32_e32 v47, 0xffff0000, v47
	v_lshlrev_b32_e32 v54, 16, v48
	v_and_b32_e32 v55, 0xffff0000, v48
	v_lshlrev_b32_e32 v48, 16, v49
	v_and_b32_e32 v49, 0xffff0000, v49
	v_pk_add_f32 v[50:51], v[40:41], v[50:51]
	v_lshl_add_u64 v[40:41], s[18:19], 0, v[42:43]
	v_pk_add_f32 v[46:47], v[32:33], v[46:47]
	v_pk_add_f32 v[48:49], v[34:35], v[48:49]
	global_load_dwordx4 v[32:35], v[40:41], off nt
	v_pk_add_f32 v[52:53], v[52:53], v[54:55]
	v_rcp_f32_e32 v54, v24
	v_mul_f32_e32 v24, v29, v56
	v_mul_f32_e32 v24, 0xbfb8aa3b, v24
	v_exp_f32_e32 v24, v24
	v_rcp_f32_e32 v55, v28
	v_add_f32_e32 v24, 1.0, v24
	v_rcp_f32_e32 v29, v24
	v_mul_f32_e32 v24, v25, v56
	v_mul_f32_e32 v24, 0xbfb8aa3b, v24
	v_exp_f32_e32 v24, v24
	s_waitcnt vmcnt(0)
	v_and_b32_e32 v59, 0xffff0000, v32
	v_add_f32_e32 v24, 1.0, v24
	v_rcp_f32_e32 v28, v24
	v_mul_f32_e32 v24, v30, v56
	v_mul_f32_e32 v24, 0xbfb8aa3b, v24
	v_exp_f32_e32 v24, v24
	v_and_b32_e32 v58, 0xffff0000, v34
	v_lshlrev_b32_e32 v60, 16, v35
	v_lshlrev_b32_e32 v61, 16, v33
	v_add_f32_e32 v24, 1.0, v24
	v_rcp_f32_e32 v25, v24
	v_mul_f32_e32 v24, v26, v56
	v_mul_f32_e32 v26, v31, v56
	v_mul_f32_e32 v26, 0xbfb8aa3b, v26
	v_exp_f32_e32 v26, v26
	v_mul_f32_e32 v24, 0xbfb8aa3b, v24
	v_exp_f32_e32 v24, v24
	v_and_b32_e32 v33, 0xffff0000, v33
	v_add_f32_e32 v26, 1.0, v26
	v_rcp_f32_e32 v31, v26
	v_mul_f32_e32 v26, v27, v56
	v_mul_f32_e32 v26, 0xbfb8aa3b, v26
	v_exp_f32_e32 v26, v26
	v_add_f32_e32 v24, 1.0, v24
	v_rcp_f32_e32 v24, v24
	v_lshlrev_b32_e32 v27, 16, v32
	v_add_f32_e32 v26, 1.0, v26
	v_rcp_f32_e32 v30, v26
	v_lshlrev_b32_e32 v26, 16, v34
	v_and_b32_e32 v32, 0xffff0000, v35
	v_mov_b32_e32 v34, v52
	v_mov_b32_e32 v35, v50
	v_pk_fma_f32 v[34:35], v[54:55], v[26:27], v[34:35]
	v_mov_b32_e32 v50, v53
	v_mov_b32_e32 v26, v48
	v_mov_b32_e32 v27, v46
	v_mov_b32_e32 v46, v49
	v_pk_fma_f32 v[50:51], v[28:29], v[58:59], v[50:51]
	v_pk_fma_f32 v[52:53], v[24:25], v[60:61], v[26:27]
	v_pk_fma_f32 v[46:47], v[30:31], v[32:33], v[46:47]
	v_lshl_add_u64 v[32:33], v[44:45], 2, s[20:21]
	s_cbranch_vccnz .LBB0_1542
	v_mov_b32_e32 v24, v35
	v_mov_b32_e32 v25, v51
	v_mov_b32_e32 v26, v53
	v_mov_b32_e32 v27, v47
	s_mov_b64 s[4:5], 0
	v_mov_b32_e32 v28, v34
	v_mov_b32_e32 v29, v50
	v_mov_b32_e32 v30, v52
	v_mov_b32_e32 v31, v46
	global_store_dwordx4 v[32:33], v[24:27], off
	global_store_dwordx4 v[32:33], v[28:31], off offset:16

; __device__ __forceinline__ float sigmoidf_(float x) { return __builtin_amdgcn_rcpf(1.f + fexp2(-1.4426950408889634f * x)); }
;     __device__ __forceinline__ void operator()(accv (&acc)[2][2][4][2], const pg8::Unit& u, int wr, int wc, int fr, int fq) const {
;     ...
;                 for (int bj = 0; bj < 2; ++bj) {
;                     const size_t off = (size_t)row * D + col0 + 128 * bj;
;                     const F8 x1 = split_load8(xhi, xlo, off); f32x4 pa, pb4; unpack8(*(const v4u*)(proj + off), pa, pb4);
;                     const accv a0 = acc[ai][bj][m][0] * rs[ai][m], a1 = acc[ai][bj][m][1] * rs[ai][m];
;                     F8 v;
; #pragma unroll
;                     for (int i = 0; i < 4; ++i) { v.a[i] = x1.a[i] + sigmoidf_(a0[i]) * pa[i]; v.b[i] = x1.b[i] + sigmoidf_(a1[i]) * pb4[i]; }
;                     if (outf) { *(f32x4*)(outf + off) = v.a; *(f32x4*)(outf + off + 4) = v.b; }
;                     else { split_store8(ohi, olo, off, v);
;                         s += ((v.a[0] * v.a[0] + v.a[1] * v.a[1]) + (v.a[2] * v.a[2] + v.a[3] * v.a[3])) + ((v.b[0] * v.b[0] + v.b[1] * v.b[1]) + (v.b[2] * v.b[2] + v.b[3] * v.b[3])); }
.LBB0_1544:
	global_load_dwordx4 v[24:27], v[36:37], off offset:256 nt
	s_nop 0
	global_load_dwordx4 v[34:37], v[38:39], off offset:256 nt
	v_mul_f32_e32 v16, v16, v56
	v_mul_f32_e32 v20, v20, v56
	v_mul_f32_e32 v16, 0xbfb8aa3b, v16
	v_mul_f32_e32 v18, v18, v56
	v_mul_f32_e32 v20, 0xbfb8aa3b, v20
	v_exp_f32_e32 v16, v16
	v_mul_f32_e32 v18, 0xbfb8aa3b, v18
	v_exp_f32_e32 v20, v20
	v_exp_f32_e32 v18, v18
	v_add_f32_e32 v16, 1.0, v16
	v_mul_f32_e32 v17, v17, v56
	v_add_f32_e32 v20, 1.0, v20
	v_add_f32_e32 v18, 1.0, v18
	v_mul_f32_e32 v17, 0xbfb8aa3b, v17
	v_mul_f32_e32 v19, v19, v56
	v_exp_f32_e32 v17, v17
	v_mul_f32_e32 v19, 0xbfb8aa3b, v19
	v_exp_f32_e32 v19, v19
	s_mov_b64 s[4:5], -1
	v_add_f32_e32 v17, 1.0, v17
	v_rcp_f32_e32 v17, v17
	v_add_f32_e32 v19, 1.0, v19
	v_rcp_f32_e32 v19, v19
	s_and_b64 vcc, exec, s[42:43]
	s_waitcnt vmcnt(1)
	v_lshlrev_b32_e32 v38, 16, v24
	v_and_b32_e32 v39, 0xffff0000, v24
	v_lshlrev_b32_e32 v24, 16, v25
	v_and_b32_e32 v25, 0xffff0000, v25
	v_lshlrev_b32_e32 v42, 16, v26
	v_and_b32_e32 v43, 0xffff0000, v26
	v_lshlrev_b32_e32 v26, 16, v27
	v_and_b32_e32 v27, 0xffff0000, v27
	s_waitcnt vmcnt(0)
	v_lshlrev_b32_e32 v46, 16, v34
	v_and_b32_e32 v47, 0xffff0000, v34
	v_lshlrev_b32_e32 v34, 16, v35
	v_and_b32_e32 v35, 0xffff0000, v35
	v_lshlrev_b32_e32 v50, 16, v37
	v_and_b32_e32 v51, 0xffff0000, v37
	v_lshlrev_b32_e32 v48, 16, v36
	v_and_b32_e32 v49, 0xffff0000, v36
	v_pk_add_f32 v[36:37], v[24:25], v[34:35]
	v_pk_add_f32 v[34:35], v[26:27], v[50:51]
	global_load_dwordx4 v[24:27], v[40:41], off offset:256 nt
	v_rcp_f32_e32 v41, v16
	v_mul_f32_e32 v16, v21, v56
	v_rcp_f32_e32 v40, v20
	v_mul_f32_e32 v16, 0xbfb8aa3b, v16
	v_mul_f32_e32 v20, v22, v56
	v_rcp_f32_e32 v21, v18
	v_mul_f32_e32 v18, v23, v56
	v_exp_f32_e32 v16, v16
	v_mul_f32_e32 v20, 0xbfb8aa3b, v20
	v_mul_f32_e32 v18, 0xbfb8aa3b, v18
	v_exp_f32_e32 v20, v20
	v_exp_f32_e32 v18, v18
	v_add_f32_e32 v16, 1.0, v16
	v_rcp_f32_e32 v16, v16
	v_add_f32_e32 v20, 1.0, v20
	v_add_f32_e32 v18, 1.0, v18
	v_rcp_f32_e32 v20, v20
	v_rcp_f32_e32 v18, v18
	v_pk_add_f32 v[38:39], v[38:39], v[46:47]
	v_pk_add_f32 v[42:43], v[42:43], v[48:49]
	s_waitcnt vmcnt(0)
	v_and_b32_e32 v47, 0xffff0000, v26
	v_and_b32_e32 v46, 0xffff0000, v24
	v_lshlrev_b32_e32 v48, 16, v25
	v_and_b32_e32 v50, 0xffff0000, v25
	v_mov_b32_e32 v25, v42
	v_mov_b32_e32 v42, v39
	v_lshlrev_b32_e32 v23, 16, v26
	v_lshlrev_b32_e32 v22, 16, v24
	v_lshlrev_b32_e32 v49, 16, v27
	v_and_b32_e32 v51, 0xffff0000, v27
	v_mov_b32_e32 v24, v38
	v_pk_fma_f32 v[26:27], v[16:17], v[46:47], v[42:43]
	v_mov_b32_e32 v16, v36
	v_mov_b32_e32 v17, v34
	v_mov_b32_e32 v34, v37
	v_pk_fma_f32 v[24:25], v[40:41], v[22:23], v[24:25]
	v_pk_fma_f32 v[38:39], v[20:21], v[48:49], v[16:17]
	v_pk_fma_f32 v[34:35], v[18:19], v[50:51], v[34:35]
	s_cbranch_vccnz .LBB0_1547
	v_mov_b32_e32 v16, v24
	v_mov_b32_e32 v17, v26
	v_mov_b32_e32 v18, v38
	v_mov_b32_e32 v19, v34
	v_mov_b32_e32 v20, v25
	v_mov_b32_e32 v21, v27
	v_mov_b32_e32 v22, v39
	v_mov_b32_e32 v23, v35
	global_store_dwordx4 v[32:33], v[16:19], off offset:512
	global_store_dwordx4 v[32:33], v[20:23], off offset:528
	s_cbranch_execz .LBB0_1548

; __device__ __forceinline__ float sigmoidf_(float x) { return __builtin_amdgcn_rcpf(1.f + fexp2(-1.4426950408889634f * x)); }
; __device__ __forceinline__ float swap_sum(float v) { auto rr = __builtin_amdgcn_permlane32_swap(__float_as_uint(v), __float_as_uint(v), false, false); return __uint_as_float(rr[0]) + __uint_as_float(rr[1]); }
; __device__ __forceinline__ void load_rstd(const float* ss, int rowb, int fq, float (&rs)[2][4]) {
;     ...
;             rs[ai][m] = __builtin_amdgcn_rsqf(s * (1.0f / D) + EPS);
;     __device__ __forceinline__ void operator()(accv (&acc)[2][2][4][2], const pg8::Unit& u, int wr, int wc, int fr, int fq) const {
;     ...
;                 const int row = rowb + 128 * ai + 16 * m; float s = 0.f;
; #pragma unroll
;                 for (int bj = 0; bj < 2; ++bj) {
;                     const size_t off = (size_t)row * D + col0 + 128 * bj;
;                     const F8 x1 = split_load8(xhi, xlo, off); f32x4 pa, pb4; unpack8(*(const v4u*)(proj + off), pa, pb4);
;                     const accv a0 = acc[ai][bj][m][0] * rs[ai][m], a1 = acc[ai][bj][m][1] * rs[ai][m];
;                     F8 v;
; #pragma unroll
;                     for (int i = 0; i < 4; ++i) { v.a[i] = x1.a[i] + sigmoidf_(a0[i]) * pa[i]; v.b[i] = x1.b[i] + sigmoidf_(a1[i]) * pb4[i]; }
;                     if (outf) { *(f32x4*)(outf + off) = v.a; *(f32x4*)(outf + off + 4) = v.b; }
;                     else { split_store8(ohi, olo, off, v);
;                         s += ((v.a[0] * v.a[0] + v.a[1] * v.a[1]) + (v.a[2] * v.a[2] + v.a[3] * v.a[3])) + ((v.b[0] * v.b[0] + v.b[1] * v.b[1]) + (v.b[2] * v.b[2] + v.b[3] * v.b[3])); }
;                 }
;                 if (!outf) { s += xshfl<16>(s); s = swap_sum(s); if (fq == 0) ssout[(size_t)row * 16 + u.pn * 4 + wc] = s; }
.LBB0_1552:
	v_add_f32_e32 v16, v208, v209
	v_fmamk_f32 v16, v16, 0x3a800000, v237
	v_rsq_f32_e32 v40, v16
	v_lshlrev_b64 v[16:17], 10, v[148:149]
	v_lshl_add_u64 v[26:27], v[16:17], 0, v[146:147]
	v_lshlrev_b64 v[24:25], 1, v[26:27]
	v_lshl_add_u64 v[20:21], s[2:3], 0, v[24:25]
	v_lshl_add_u64 v[22:23], s[10:11], 0, v[24:25]
	global_load_dwordx4 v[16:19], v[20:21], off nt
	global_load_dwordx4 v[28:31], v[22:23], off nt
	v_mul_f32_e32 v8, v8, v40
	v_mul_f32_e32 v8, 0xbfb8aa3b, v8
	v_exp_f32_e32 v8, v8
	v_mul_f32_e32 v12, v12, v40
	v_mul_f32_e32 v12, 0xbfb8aa3b, v12
	v_exp_f32_e32 v12, v12
	v_add_f32_e32 v8, 1.0, v8
	s_mov_b64 s[4:5], -1
	s_and_b64 vcc, exec, s[42:43]
	v_add_f32_e32 v12, 1.0, v12
	s_waitcnt vmcnt(1)
	v_lshlrev_b32_e32 v32, 16, v16
	v_and_b32_e32 v33, 0xffff0000, v16
	v_lshlrev_b32_e32 v16, 16, v17
	v_and_b32_e32 v17, 0xffff0000, v17
	s_waitcnt vmcnt(0)
	v_lshlrev_b32_e32 v34, 16, v28
	v_and_b32_e32 v35, 0xffff0000, v28
	v_lshlrev_b32_e32 v28, 16, v29
	v_and_b32_e32 v29, 0xffff0000, v29
	v_lshlrev_b32_e32 v36, 16, v18
	v_and_b32_e32 v37, 0xffff0000, v18
	v_lshlrev_b32_e32 v18, 16, v19
	v_and_b32_e32 v19, 0xffff0000, v19
	v_lshlrev_b32_e32 v38, 16, v30
	v_and_b32_e32 v39, 0xffff0000, v30
	v_lshlrev_b32_e32 v42, 16, v31
	v_and_b32_e32 v43, 0xffff0000, v31
	v_pk_add_f32 v[30:31], v[16:17], v[28:29]
	v_lshl_add_u64 v[28:29], s[18:19], 0, v[24:25]
	v_pk_add_f32 v[34:35], v[32:33], v[34:35]
	v_pk_add_f32 v[32:33], v[18:19], v[42:43]
	global_load_dwordx4 v[16:19], v[28:29], off nt
	v_pk_add_f32 v[36:37], v[36:37], v[38:39]
	v_rcp_f32_e32 v38, v8
	v_mul_f32_e32 v8, v13, v40
	v_mul_f32_e32 v8, 0xbfb8aa3b, v8
	v_exp_f32_e32 v8, v8
	v_rcp_f32_e32 v39, v12
	v_add_f32_e32 v8, 1.0, v8
	v_rcp_f32_e32 v13, v8
	v_mul_f32_e32 v8, v9, v40
	v_mul_f32_e32 v8, 0xbfb8aa3b, v8
	v_exp_f32_e32 v8, v8
	s_waitcnt vmcnt(0)
	v_and_b32_e32 v43, 0xffff0000, v16
	v_add_f32_e32 v8, 1.0, v8
	v_rcp_f32_e32 v12, v8
	v_mul_f32_e32 v8, v14, v40
	v_mul_f32_e32 v8, 0xbfb8aa3b, v8
	v_exp_f32_e32 v8, v8
	v_and_b32_e32 v42, 0xffff0000, v18
	v_lshlrev_b32_e32 v44, 16, v19
	v_lshlrev_b32_e32 v45, 16, v17
	v_add_f32_e32 v8, 1.0, v8
	v_rcp_f32_e32 v9, v8
	v_mul_f32_e32 v8, v10, v40
	v_mul_f32_e32 v10, v15, v40
	v_mul_f32_e32 v10, 0xbfb8aa3b, v10
	v_exp_f32_e32 v10, v10
	v_mul_f32_e32 v8, 0xbfb8aa3b, v8
	v_exp_f32_e32 v8, v8
	v_and_b32_e32 v17, 0xffff0000, v17
	v_add_f32_e32 v10, 1.0, v10
	v_rcp_f32_e32 v15, v10
	v_mul_f32_e32 v10, v11, v40
	v_mul_f32_e32 v10, 0xbfb8aa3b, v10
	v_exp_f32_e32 v10, v10
	v_add_f32_e32 v8, 1.0, v8
	v_rcp_f32_e32 v8, v8
	v_lshlrev_b32_e32 v11, 16, v16
	v_add_f32_e32 v10, 1.0, v10
	v_rcp_f32_e32 v14, v10
	v_lshlrev_b32_e32 v10, 16, v18
	v_and_b32_e32 v16, 0xffff0000, v19
	v_mov_b32_e32 v18, v36
	v_mov_b32_e32 v19, v34
	v_pk_fma_f32 v[18:19], v[38:39], v[10:11], v[18:19]
	v_mov_b32_e32 v34, v37
	v_mov_b32_e32 v10, v32
	v_mov_b32_e32 v11, v30
	v_mov_b32_e32 v30, v33
	v_pk_fma_f32 v[34:35], v[12:13], v[42:43], v[34:35]
	v_pk_fma_f32 v[36:37], v[8:9], v[44:45], v[10:11]
	v_pk_fma_f32 v[30:31], v[14:15], v[16:17], v[30:31]
	v_lshl_add_u64 v[16:17], v[26:27], 2, s[20:21]
	s_cbranch_vccnz .LBB0_1554
	v_mov_b32_e32 v8, v19
	v_mov_b32_e32 v9, v35
	v_mov_b32_e32 v10, v37
	v_mov_b32_e32 v11, v31
	s_mov_b64 s[4:5], 0
	v_mov_b32_e32 v12, v18
	v_mov_b32_e32 v13, v34
	v_mov_b32_e32 v14, v36
	v_mov_b32_e32 v15, v30
	global_store_dwordx4 v[16:17], v[8:11], off
	global_store_dwordx4 v[16:17], v[12:15], off offset:16

; __device__ __forceinline__ float sigmoidf_(float x) { return __builtin_amdgcn_rcpf(1.f + fexp2(-1.4426950408889634f * x)); }
;     __device__ __forceinline__ void operator()(accv (&acc)[2][2][4][2], const pg8::Unit& u, int wr, int wc, int fr, int fq) const {
;     ...
;                 for (int bj = 0; bj < 2; ++bj) {
;                     const size_t off = (size_t)row * D + col0 + 128 * bj;
;                     const F8 x1 = split_load8(xhi, xlo, off); f32x4 pa, pb4; unpack8(*(const v4u*)(proj + off), pa, pb4);
;                     const accv a0 = acc[ai][bj][m][0] * rs[ai][m], a1 = acc[ai][bj][m][1] * rs[ai][m];
;                     F8 v;
; #pragma unroll
;                     for (int i = 0; i < 4; ++i) { v.a[i] = x1.a[i] + sigmoidf_(a0[i]) * pa[i]; v.b[i] = x1.b[i] + sigmoidf_(a1[i]) * pb4[i]; }
;                     if (outf) { *(f32x4*)(outf + off) = v.a; *(f32x4*)(outf + off + 4) = v.b; }
;                     else { split_store8(ohi, olo, off, v);
;                         s += ((v.a[0] * v.a[0] + v.a[1] * v.a[1]) + (v.a[2] * v.a[2] + v.a[3] * v.a[3])) + ((v.b[0] * v.b[0] + v.b[1] * v.b[1]) + (v.b[2] * v.b[2] + v.b[3] * v.b[3])); }
.LBB0_1556:
	global_load_dwordx4 v[12:15], v[20:21], off offset:256 nt
	s_nop 0
	global_load_dwordx4 v[18:21], v[22:23], off offset:256 nt
	s_nop 0
	global_load_dwordx4 v[22:25], v[28:29], off offset:256 nt
	v_mul_f32_e32 v4, v4, v40
	v_mul_f32_e32 v0, v0, v40
	v_mul_f32_e32 v5, v5, v40
	v_mul_f32_e32 v1, v1, v40
	v_mul_f32_e32 v6, v6, v40
	v_mul_f32_e32 v2, v2, v40
	v_mul_f32_e32 v7, v7, v40
	v_mul_f32_e32 v3, v3, v40
	v_mul_f32_e32 v4, 0xbfb8aa3b, v4
	v_mul_f32_e32 v0, 0xbfb8aa3b, v0
	v_mul_f32_e32 v5, 0xbfb8aa3b, v5
	v_mul_f32_e32 v1, 0xbfb8aa3b, v1
	v_mul_f32_e32 v6, 0xbfb8aa3b, v6
	v_mul_f32_e32 v2, 0xbfb8aa3b, v2
	v_mul_f32_e32 v7, 0xbfb8aa3b, v7
	v_mul_f32_e32 v3, 0xbfb8aa3b, v3
	v_exp_f32_e32 v4, v4
	v_exp_f32_e32 v0, v0
	v_exp_f32_e32 v5, v5
	v_exp_f32_e32 v1, v1
	v_exp_f32_e32 v6, v6
	v_exp_f32_e32 v2, v2
	v_exp_f32_e32 v7, v7
	v_exp_f32_e32 v3, v3
	v_add_f32_e32 v4, 1.0, v4
	v_add_f32_e32 v27, 1.0, v0
	v_add_f32_e32 v5, 1.0, v5
	v_add_f32_e32 v28, 1.0, v1
	v_add_f32_e32 v6, 1.0, v6
	v_add_f32_e32 v29, 1.0, v2
	v_add_f32_e32 v7, 1.0, v7
	v_add_f32_e32 v30, 1.0, v3
	v_rcp_f32_e32 v0, v4
	v_rcp_f32_e32 v1, v27
	v_rcp_f32_e32 v2, v5
	v_rcp_f32_e32 v3, v28
	v_rcp_f32_e32 v4, v6
	v_rcp_f32_e32 v5, v29
	v_rcp_f32_e32 v6, v7
	v_rcp_f32_e32 v7, v30
	s_and_b64 vcc, exec, s[42:43]
	s_mov_b64 s[4:5], -1
	s_waitcnt vmcnt(2)
	v_lshlrev_b32_e32 v28, 16, v12
	v_and_b32_e32 v29, 0xffff0000, v12
	v_lshlrev_b32_e32 v12, 16, v13
	v_and_b32_e32 v13, 0xffff0000, v13
	v_lshlrev_b32_e32 v30, 16, v14
	v_and_b32_e32 v31, 0xffff0000, v14
	v_lshlrev_b32_e32 v14, 16, v15
	v_and_b32_e32 v15, 0xffff0000, v15
	s_waitcnt vmcnt(1)
	v_lshlrev_b32_e32 v32, 16, v18
	v_and_b32_e32 v33, 0xffff0000, v18
	v_lshlrev_b32_e32 v18, 16, v19
	v_and_b32_e32 v19, 0xffff0000, v19
	v_lshlrev_b32_e32 v34, 16, v20
	v_and_b32_e32 v35, 0xffff0000, v20
	v_lshlrev_b32_e32 v20, 16, v21
	v_and_b32_e32 v21, 0xffff0000, v21
	v_pk_add_f32 v[12:13], v[12:13], v[18:19]
	v_pk_add_f32 v[18:19], v[28:29], v[32:33]
	v_pk_add_f32 v[20:21], v[14:15], v[20:21]
	v_pk_add_f32 v[14:15], v[30:31], v[34:35]
	s_waitcnt vmcnt(0)
	v_lshlrev_b32_e32 v37, 16, v24
	v_lshlrev_b32_e32 v36, 16, v22
	v_and_b32_e32 v39, 0xffff0000, v24
	v_and_b32_e32 v38, 0xffff0000, v22
	v_lshlrev_b32_e32 v41, 16, v25
	v_lshlrev_b32_e32 v40, 16, v23
	v_and_b32_e32 v25, 0xffff0000, v25
	v_and_b32_e32 v24, 0xffff0000, v23
	v_mov_b32_e32 v22, v18
	v_mov_b32_e32 v23, v14
	v_mov_b32_e32 v14, v19
	v_mov_b32_e32 v28, v12
	v_mov_b32_e32 v29, v20
	v_mov_b32_e32 v20, v13
	v_pk_fma_f32 v[12:13], v[0:1], v[36:37], v[22:23]
	v_pk_fma_f32 v[18:19], v[2:3], v[38:39], v[14:15]
	v_pk_fma_f32 v[14:15], v[4:5], v[40:41], v[28:29]
	v_pk_fma_f32 v[20:21], v[6:7], v[24:25], v[20:21]
	s_cbranch_vccnz .LBB0_1559
	v_mov_b32_e32 v0, v12
	v_mov_b32_e32 v1, v18
	v_mov_b32_e32 v2, v14
	v_mov_b32_e32 v3, v20
	v_mov_b32_e32 v4, v13
	v_mov_b32_e32 v5, v19
	v_mov_b32_e32 v6, v15
	v_mov_b32_e32 v7, v21
	global_store_dwordx4 v[16:17], v[0:3], off offset:512
	global_store_dwordx4 v[16:17], v[4:7], off offset:528
	s_cbranch_execz .LBB0_1560
